# retention-state item fused into the RG-LRU chunk loop (hand-written state step, loads issued one chunk ahead)
# speedup vs baseline: 1.0344x; 1.0102x over previous
; __device__ __forceinline__ void refresh(Frame& F) { int t = threadIdx.x; asm volatile("" : "+v"(t)); F.tid = t; F.lane = t & 63; F.wave = __builtin_amdgcn_readfirstlane(t >> 6); }
; #define ST_LOAD(KS, VS, mc_) do { const int _p0 = 128 * (mc_); _Pragma("unroll") for (int ks = 0; ks < 4; ++ks) { VS[ks] = *(const bf16x8*)(vbase + _p0 + 32 * ks + 8 * fq); \
;         _Pragma("unroll") for (int t = 0; t < 2; ++t) KS[ks][t] = *(const bf16x8*)(kbase + (size_t)(16 * t) * TB + _p0 + 32 * ks + 8 * fq); } } while (0)
; __device__ __forceinline__ void ret_state_item(const Args& A, Frame& F, int l, int it) {
;     refresh(F);
;     const int dvh = it & 1, dir = (it >> 1) & 1, h = (it >> 2) & 7, b = it >> 5;
;     const int lane = F.lane, fr = lane & 15, fq = lane >> 4, w = F.wave, dvt = w & 3, dkh = w >> 2;
;     const float l2g = log2_gamma(A, F, l, dir, h);
;     const float cdec = exp2f(128.f * l2g);
;     float dec[4][8];
; #pragma unroll
;     for (int ks = 0; ks < 4; ++ks)
; #pragma unroll
;         for (int s = 0; s < 8; ++s) { const int a = 32 * ks + 8 * fq + s; dec[ks][s] = exp2f(l2g * (float)(dir ? a : 127 - a)); }
;     const int dvrow = 64 * dvh + 16 * dvt + fr;
;     const bf16_t* kbase = WSB(WS_KT) + ((size_t)(b * NH + h) * DK + 32 * dkh + fr) * TB;
;     const bf16_t* vbase = WSB(WS_VT) + ((size_t)(b * NH + h) * DV + dvrow) * TB;
;     f32x4 acc[2];
;     acc[0] = (f32x4){0.f, 0.f, 0.f, 0.f}; acc[1] = acc[0];
;     bf16x8 ka[4][2], va[4], kb2[4][2], vb2[4];
;     ...
;     ST_LOAD(ka, va, ST_MC(0));
;     for (int s2 = 0; s2 < NCH; s2 += 2) {
;         ST_STORE(ST_MC(s2));
;         { const int sn = s2 + 1 < NCH - 1 ? s2 + 1 : NCH - 2; ST_LOAD(kb2, vb2, ST_MC(sn)); }
;         ST_COMPUTE(ka, va);
;         ST_STORE(ST_MC(s2 + 1));
;         if (s2 + 1 == NCH - 1) break;
;         { const int sn = s2 + 2 < NCH - 1 ? s2 + 2 : NCH - 2; ST_LOAD(ka, va, ST_MC(sn)); }
;         ST_COMPUTE(kb2, vb2);
;     }
;     ...
; }
; __global__ void __launch_bounds__(NTHREADS) mega(Args args) {
;     ...
;                 for (int it = F.bid; it < 512; it += F.G) { if (it < 256) lru_item(args, F, l, it); else ret_state_item(args, F, l, it - 256); }
.LBB0_44:
	s_cmpk_gt_i32 s37, 0xff
	s_cbranch_scc0 .LBB0_49
	s_branch .LBB0_43

; #define LAS __attribute__((address_space(3)))
; __device__ __forceinline__ void refresh(Frame& F) { int t = threadIdx.x; asm volatile("" : "+v"(t)); F.tid = t; F.lane = t & 63; F.wave = __builtin_amdgcn_readfirstlane(t >> 6); }
; __device__ __forceinline__ void ret_state_item(const Args& A, Frame& F, int l, int it) {
;     ...
;     const int dvh = it & 1, dir = (it >> 1) & 1, h = (it >> 2) & 7, b = it >> 5;
;     const int lane = F.lane, fr = lane & 15, fq = lane >> 4, w = F.wave, dvt = w & 3, dkh = w >> 2;
;     const float l2g = log2_gamma(A, F, l, dir, h);
;     const float cdec = exp2f(128.f * l2g);
;     float dec[4][8];
; #pragma unroll
;     for (int ks = 0; ks < 4; ++ks)
; #pragma unroll
;         for (int s = 0; s < 8; ++s) { const int a = 32 * ks + 8 * fq + s; dec[ks][s] = exp2f(l2g * (float)(dir ? a : 127 - a)); }
;     const int dvrow = 64 * dvh + 16 * dvt + fr;
;     const bf16_t* kbase = WSB(WS_KT) + ((size_t)(b * NH + h) * DK + 32 * dkh + fr) * TB;
;     const bf16_t* vbase = WSB(WS_VT) + ((size_t)(b * NH + h) * DV + dvrow) * TB;
;     f32x4 acc[2];
;     acc[0] = (f32x4){0.f, 0.f, 0.f, 0.f}; acc[1] = acc[0];
;     bf16x8 ka[4][2], va[4], kb2[4][2], vb2[4];
; __device__ __forceinline__ void lru_item(const Args& A, Frame& F, int l, int it) {
;     refresh(F);
;     const int blk = it & 15, dir = (it >> 4) & 1, b = it >> 5;
;     const int tid = F.tid, lane = F.lane, fr = lane & 15, fq = lane >> 4, w = F.wave;
;     LAS float* us = (LAS float*)F.lds;
;     LAS float* as = us + 128 * 64;
;     LAS bf16_t* ub = (LAS bf16_t*)(F.lds + 65536);
;     LAS bf16_t* wgs = (LAS bf16_t*)(F.lds + 65536 + 18432);
;     LAS float* segA = (LAS float*)(F.lds + 65536 + 2 * 18432);
;     LAS float* segB = segA + 512;
;     LAS float* hcar = segA + 2048;
;     __syncthreads();
.LBB0_51:
	v_readfirstlane_b32 s2, v138
	s_and_b32 s8, s37, 1
	s_bfe_u32 s10, s37, 0x10001
	s_lshr_b32 s9, s37, 2
	s_and_b32 s12, s9, 7
	s_lshr_b32 s2, s2, 6
	s_lshl_b32 s13, s10, 3
	s_add_i32 s13, s13, s12
	s_add_i32 s13, s13, s53
	s_lshl_b32 s13, s13, 2
	s_load_dwordx2 s[100:101], s[46:47], 0x60
	s_waitcnt lgkmcnt(0)
	s_load_dword s5, s[100:101], s13
	s_lshr_b32 s15, s2, 2
	s_and_b32 s18, s2, 3
	s_cmp_eq_u32 s10, 0
	s_cselect_b32 s14, -1, 1
	s_waitcnt lgkmcnt(0)
	v_mov_b32_e32 v250, s5
	v_and_b32_e32 v251, 0x7fffffff, v250
	v_mul_f32_e32 v251, 0xbfb8aa3b, v251
	v_exp_f32_e32 v251, v251
	v_mov_b32_e32 v252, 0x3e4ccccd
	v_fmaak_f32 v252, v251, v252, 0xbe800000
	v_fmaak_f32 v252, v251, v252, 0x3eaaaaab
	v_fmaak_f32 v252, v251, v252, 0xbf000000
	v_fmaak_f32 v252, v251, v252, 0x3f800000
	v_mul_f32_e32 v252, v251, v252
	v_add_f32_e32 v253, 1.0, v251
	v_log_f32_e32 v253, v253
	v_cmp_gt_f32_e32 vcc, 0x3c800000, v251
	v_mul_f32_e32 v253, 0x3f317218, v253
	s_nop 1
	v_cndmask_b32_e32 v252, v253, v252, vcc
	v_max_f32_e64 v253, -v250, 0
	v_add_f32_e32 v252, v253, v252
	v_mul_f32_e32 v252, 0xbfb8aa3b, v252
	v_mul_f32_e32 v168, 0x43000000, v252
	v_exp_f32_e32 v168, v168
	v_and_b32_e32 v141, 63, v138
	v_and_b32_e32 v137, 15, v141
	v_lshrrev_b32_e32 v141, 4, v141
	s_cmp_eq_u32 s10, 0
	s_cselect_b32 s4, 0x7f, 0
	v_mov_b32_e32 v143, s14
	v_lshlrev_b32_e32 v255, 3, v141
	v_mad_i32_i24 v255, v143, v255, s4
	v_mad_i32_i24 v250, v143, 0, v255
	v_cvt_f32_i32_e32 v250, v250
	v_mul_f32_e32 v250, v252, v250
	v_exp_f32_e32 v152, v250
	v_mad_i32_i24 v250, v143, 1, v255
	v_cvt_f32_i32_e32 v250, v250
	v_mul_f32_e32 v250, v252, v250
	v_exp_f32_e32 v153, v250
	v_mad_i32_i24 v250, v143, 2, v255
	v_cvt_f32_i32_e32 v250, v250
	v_mul_f32_e32 v250, v252, v250
	v_exp_f32_e32 v154, v250
	v_mad_i32_i24 v250, v143, 3, v255
	v_cvt_f32_i32_e32 v250, v250
	v_mul_f32_e32 v250, v252, v250
	v_exp_f32_e32 v155, v250
	v_mad_i32_i24 v250, v143, 4, v255
	v_cvt_f32_i32_e32 v250, v250
	v_mul_f32_e32 v250, v252, v250
	v_exp_f32_e32 v156, v250
	v_mad_i32_i24 v250, v143, 5, v255
	v_cvt_f32_i32_e32 v250, v250
	v_mul_f32_e32 v250, v252, v250
	v_exp_f32_e32 v157, v250
	v_mad_i32_i24 v250, v143, 6, v255
	v_cvt_f32_i32_e32 v250, v250
	v_mul_f32_e32 v250, v252, v250
	v_exp_f32_e32 v158, v250
	v_mad_i32_i24 v250, v143, 7, v255
	v_cvt_f32_i32_e32 v250, v250
	v_mul_f32_e32 v250, v252, v250
	v_exp_f32_e32 v159, v250
	s_lshl_b32 s4, s14, 5
	v_cvt_f32_i32_e32 v250, s4
	v_mul_f32_e32 v250, v252, v250
	v_add_f32_e32 v251, v250, v250
	v_add_f32_e32 v253, v251, v250
	v_exp_f32_e32 v244, v250
	v_exp_f32_e32 v246, v251
	v_exp_f32_e32 v248, v253
	s_lshl_b32 s4, s9, 6
	s_lshl_b32 s5, s15, 5
	s_add_i32 s4, s4, s5
	s_mulk_i32 s4, 0x1200
	v_mul_u32_u24_e32 v169, 0x1200, v137
	v_lshl_add_u32 v169, v141, 4, v169
	v_add_u32_e32 v169, s4, v169
	s_lshl_b32 s5, s8, 6
	s_lshl_b32 s18, s18, 4
	s_add_i32 s18, s18, s5
	s_lshl_b32 s4, s9, 7
	s_add_i32 s4, s4, s18
	s_mulk_i32 s4, 0x1200
	v_mul_u32_u24_e32 v242, 0x1200, v137
	v_lshl_add_u32 v242, v141, 4, v242
	v_add_u32_e32 v242, s4, v242
	s_lshl_b32 s4, s9, 1
	s_add_i32 s4, s4, s10
	s_mulk_i32 s4, 0x900
	s_add_i32 s4, s4, s18
	s_lshl_b32 s4, s4, 7
	s_lshl_b32 s5, s15, 6
	s_add_i32 s4, s4, s5
	v_lshlrev_b32_e32 v243, 7, v137
	v_lshl_add_u32 v243, v141, 3, v243
	v_add_u32_e32 v243, s4, v243
	v_mov_b32_e32 v160, 0
	v_mov_b32_e32 v161, 0
	v_mov_b32_e32 v162, 0
	v_mov_b32_e32 v163, 0
	v_mov_b32_e32 v164, 0
	v_mov_b32_e32 v165, 0
	v_mov_b32_e32 v166, 0
	v_mov_b32_e32 v167, 0
	s_bfe_u32 s45, s37, 0x10004
	v_mov_b32_e32 v54, v138
	s_or_b32 s4, s45, s85
	s_movk_i32 s8, 0x2000
	s_and_b32 s39, s37, 15
	v_and_b32_e32 v102, 63, v54
	v_readfirstlane_b32 s2, v54
	s_ashr_i32 s5, s4, 31
	v_cmp_gt_i32_e32 vcc, s8, v54
	s_barrier
	s_and_saveexec_b64 s[8:9], vcc
	s_mov_b32 s18, 0x33800000
	s_mov_b32 s19, 0x3f317218
	s_cbranch_execz .LBB0_59
	s_load_dwordx2 s[10:11], s[46:47], 0x80
	v_max_i32_e32 v0, 0x1e00, v54
	s_lshl_b64 s[12:13], s[4:5], 19
	v_sub_u32_e32 v0, v0, v54
	v_add_u32_e32 v0, 0x1ff, v0
	s_waitcnt lgkmcnt(0)
	s_add_u32 s10, s10, s12
	s_movk_i32 s12, 0x1ff
	s_addc_u32 s11, s11, s13
	v_cmp_lt_u32_e32 vcc, s12, v0
	s_mov_b64 s[14:15], -1
	s_waitcnt vmcnt(0)
	v_mov_b32_e32 v3, v54
	s_and_saveexec_b64 s[12:13], vcc
	s_cbranch_execz .LBB0_56
	v_lshrrev_b32_e32 v0, 9, v0
	v_add_u32_e32 v2, 1, v0
	v_and_b32_e32 v6, 0xfffffe, v2
	v_add_u32_e32 v55, 0x200, v54
	s_mov_b32 s26, s39
	v_mov_b32_e32 v3, v102
	s_mov_b64 s[14:15], 0
	v_mov_b32_e32 v7, v6
	v_mov_b64_e32 v[4:5], v[54:55]

; __device__ __forceinline__ float softplusf_(float x) { return fmaxf(x, 0.f) + log1pf(expf(-fabsf(x))); }
; __device__ __forceinline__ void lru_item(const Args& A, Frame& F, int l, int it) {
;     ...
;         if (tid < 128) hcar[tid] = 0.f;
;     }
;     float bgr[4], bgi[4], spl[4];
; #pragma unroll
;     for (int nt = 0; nt < 4; ++nt) {
;         const int ch = blk * 64 + 16 * nt + fr;
;         bgr[nt] = GIN(17)[((size_t)(l * 2 + dir) * 2 + 0) * D + ch];
;         bgi[nt] = GIN(17)[((size_t)(l * 2 + dir) * 2 + 1) * D + ch];
;         spl[nt] = -8.f * 1.4426950408889634f * softplusf_(-GIN(18)[(size_t)(l * 2 + dir) * D + ch]);
;     }
.LBB0_59:
	s_or_b64 exec, exec, s[8:9]
	s_movk_i32 s8, 0x80
	v_cmp_gt_i32_e32 vcc, s8, v54
	s_and_saveexec_b64 s[8:9], vcc
	v_lshl_add_u32 v0, v54, 2, 0
	v_add_u32_e32 v0, 0x1b000, v0
	ds_write_b32 v0, v1
	s_or_b64 exec, exec, s[8:9]
	s_load_dwordx4 s[8:11], s[46:47], 0x88
	s_ashr_i32 s26, s2, 6
	s_ashr_i32 s14, s37, 5
	s_lshl_b32 s15, s39, 6
	s_lshl_b64 s[12:13], s[4:5], 13
	s_waitcnt lgkmcnt(0)
	s_add_u32 s12, s8, s12
	s_waitcnt vmcnt(0)
	v_and_b32_e32 v22, 15, v54
	s_addc_u32 s13, s9, s13
	s_lshl_b64 s[4:5], s[4:5], 12
	v_or_b32_e32 v0, s15, v22
	s_add_u32 s4, s10, s4
	s_addc_u32 s5, s11, s5
	v_lshlrev_b32_e32 v0, 2, v0
	global_load_dword v7, v0, s[4:5]
	global_load_dword v4, v0, s[4:5] offset:64
	v_lshl_add_u64 v[2:3], s[12:13], 0, v[0:1]
	s_movk_i32 s20, 0x1000
	v_add_co_u32_e32 v2, vcc, s20, v2
	s_load_dwordx4 s[8:11], s[46:47], 0x70
	s_nop 0
	v_addc_co_u32_e32 v3, vcc, 0, v3, vcc
	global_load_dword v55, v0, s[12:13]
	global_load_dword v59, v0, s[12:13] offset:64
	global_load_dword v78, v0, s[12:13] offset:128
	global_load_dword v6, v0, s[4:5] offset:128
	global_load_dword v5, v0, s[4:5] offset:192
	global_load_dword v79, v0, s[12:13] offset:192
	s_mov_b32 s5, 0x3f2aaaab
	s_mov_b32 s4, 0x7f800000
	global_load_dword v83, v[2:3], off
	global_load_dword v84, v[2:3], off offset:64
	global_load_dword v85, v[2:3], off offset:128
	global_load_dword v86, v[2:3], off offset:192
	s_mov_b32 s12, 0x33800000
	v_ashrrev_i32_e32 v32, 2, v54
	v_and_b32_e32 v88, -4, v32
	v_or_b32_e32 v90, 3, v32
	v_ashrrev_i32_e32 v91, 6, v54
	s_mov_b32 s2, 0
	s_mov_b32 s20, 0x3f317218
	s_mov_b32 s29, 0x7f800000
	s_mov_b64 s[78:79], 0
	s_waitcnt vmcnt(11)
	v_mul_f32_e64 v8, |v7|, s59
	v_fma_f32 v11, |v7|, s59, -v8
	v_rndne_f32_e32 v12, v8
	v_fma_f32 v11, |v7|, s76, v11
	v_sub_f32_e32 v8, v8, v12
	v_add_f32_e32 v8, v8, v11
	v_cvt_i32_f32_e32 v12, v12
	v_exp_f32_e32 v8, v8
	s_waitcnt vmcnt(10)
	v_max_f32_e64 v9, -v4, -v4
	v_mul_f32_e64 v10, |v4|, s59
	v_cmp_ngt_f32_e64 vcc, |v7|, s77
	v_ldexp_f32 v8, v8, v12
	v_max_f32_e32 v13, 0, v9
	v_fma_f32 v9, |v4|, s59, -v10
	v_rndne_f32_e32 v14, v10
	v_cndmask_b32_e32 v8, 0, v8, vcc
	v_cmp_nlt_f32_e64 vcc, |v7|, s58
	v_max_f32_e64 v0, -v7, -v7
	v_fma_f32 v9, |v4|, s76, v9
	v_sub_f32_e32 v10, v10, v14
	v_cndmask_b32_e32 v7, v182, v8, vcc
	v_add_f32_e32 v9, v10, v9
	v_add_f32_e32 v12, 1.0, v7
	v_cvt_i32_f32_e32 v11, v14
	v_exp_f32_e32 v10, v9
	v_add_f32_e32 v14, -1.0, v12
	v_frexp_mant_f32_e32 v15, v12
	v_cvt_f64_f32_e32 v[8:9], v12
	v_sub_f32_e32 v16, v14, v12
	v_frexp_exp_i32_f64_e32 v8, v[8:9]
	v_cmp_gt_f32_e32 vcc, s5, v15
	v_sub_f32_e32 v14, v7, v14
	v_add_f32_e32 v9, 1.0, v16
	v_subbrev_co_u32_e32 v8, vcc, 0, v8, vcc
	v_add_f32_e32 v9, v14, v9
	v_sub_u32_e32 v14, 0, v8
	v_cvt_f32_i32_e32 v8, v8
	v_ldexp_f32 v12, v12, v14
	v_ldexp_f32 v9, v9, v14
	v_add_f32_e32 v14, -1.0, v12
	v_add_f32_e32 v15, 1.0, v12
	v_add_f32_e32 v16, 1.0, v14
	v_add_f32_e32 v17, -1.0, v15
	v_sub_f32_e32 v16, v12, v16
	v_sub_f32_e32 v12, v12, v17
	v_mul_f32_e32 v17, 0x3f317218, v8
	v_add_f32_e32 v16, v9, v16
	v_add_f32_e32 v9, v9, v12
	v_fma_f32 v12, v8, s19, -v17
	v_add_f32_e32 v18, v14, v16
	v_add_f32_e32 v19, v15, v9
	v_fmac_f32_e32 v12, 0xb102e308, v8
	v_sub_f32_e32 v8, v14, v18
	v_sub_f32_e32 v14, v15, v19
	v_rcp_f32_e32 v15, v19
	v_add_f32_e32 v20, v17, v12
	v_add_f32_e32 v9, v9, v14
	v_sub_f32_e32 v14, v20, v17
	v_sub_f32_e32 v12, v12, v14
	v_mul_f32_e32 v14, v18, v15
	v_add_f32_e32 v8, v16, v8
	v_mul_f32_e32 v16, v19, v14
	v_fma_f32 v17, v14, v19, -v16
	v_fmac_f32_e32 v17, v14, v9
	v_add_f32_e32 v21, v16, v17
	v_sub_f32_e32 v23, v18, v21
	v_sub_f32_e32 v16, v21, v16
	v_sub_f32_e32 v18, v18, v23
	v_sub_f32_e32 v16, v16, v17
	v_sub_f32_e32 v17, v18, v21
	v_add_f32_e32 v8, v8, v17
	v_add_f32_e32 v8, v16, v8
	v_add_f32_e32 v16, v23, v8
	v_mul_f32_e32 v17, v15, v16
	v_sub_f32_e32 v18, v23, v16
	v_mul_f32_e32 v21, v19, v17
	v_add_f32_e32 v8, v8, v18
	v_add_f32_e32 v18, v14, v17
	v_fma_f32 v19, v17, v19, -v21
	v_sub_f32_e32 v14, v18, v14
	v_fmac_f32_e32 v19, v17, v9
	v_sub_f32_e32 v9, v17, v14
	v_add_f32_e32 v14, v21, v19
	v_sub_f32_e32 v17, v14, v21
	v_sub_f32_e32 v21, v16, v14
	v_sub_f32_e32 v16, v16, v21
	v_sub_f32_e32 v14, v16, v14
	v_sub_f32_e32 v17, v17, v19
	v_add_f32_e32 v8, v8, v14
	v_add_f32_e32 v8, v17, v8
	v_add_f32_e32 v8, v21, v8
	v_mul_f32_e32 v8, v15, v8
	v_add_f32_e32 v8, v9, v8
	v_add_f32_e32 v9, v18, v8
	v_mul_f32_e32 v14, v9, v9
	v_fmamk_f32 v17, v14, 0x3e9b6dac, v171
	v_sub_f32_e32 v15, v9, v18
	v_ldexp_f32 v16, v9, 1
	v_mul_f32_e32 v9, v9, v14
	v_fmaak_f32 v14, v14, v17, 0x3f2aaada
	v_mul_f32_e32 v9, v9, v14
	v_add_f32_e32 v14, v16, v9
	v_sub_f32_e32 v8, v8, v15
	v_sub_f32_e32 v15, v14, v16
	v_ldexp_f32 v8, v8, 1
	v_sub_f32_e32 v9, v9, v15
	v_add_f32_e32 v8, v8, v9
	v_add_f32_e32 v9, v14, v8
	v_sub_f32_e32 v14, v9, v14
	v_add_f32_e32 v15, v20, v9
	v_sub_f32_e32 v8, v8, v14
	v_sub_f32_e32 v14, v15, v20
	v_sub_f32_e32 v16, v15, v14
	v_sub_f32_e32 v9, v9, v14
	v_add_f32_e32 v14, v12, v8
	v_sub_f32_e32 v16, v20, v16
	v_sub_f32_e32 v17, v14, v12
	v_add_f32_e32 v9, v9, v16
	v_sub_f32_e32 v16, v14, v17
	v_sub_f32_e32 v8, v8, v17
	v_sub_f32_e32 v12, v12, v16
	v_add_f32_e32 v9, v14, v9
	v_add_f32_e32 v8, v8, v12
	v_add_f32_e32 v12, v15, v9
	v_sub_f32_e32 v14, v12, v15
	v_sub_f32_e32 v9, v9, v14
	v_add_f32_e32 v8, v8, v9
	v_add_f32_e32 v8, v12, v8
	v_cmp_neq_f32_e32 vcc, s4, v7
	v_max_f32_e32 v0, 0, v0
	s_waitcnt vmcnt(5)
; __device__ __forceinline__ float softplusf_(float x) { return fmaxf(x, 0.f) + log1pf(expf(-fabsf(x))); }
; __device__ __forceinline__ void lru_item(const Args& A, Frame& F, int l, int it) {
;     ...
;     for (int nt = 0; nt < 4; ++nt) {
;         const int ch = blk * 64 + 16 * nt + fr;
;         bgr[nt] = GIN(17)[((size_t)(l * 2 + dir) * 2 + 0) * D + ch];
;         bgi[nt] = GIN(17)[((size_t)(l * 2 + dir) * 2 + 1) * D + ch];
;         spl[nt] = -8.f * 1.4426950408889634f * softplusf_(-GIN(18)[(size_t)(l * 2 + dir) * D + ch]);
;     }
	v_max_f32_e64 v2, -v5, -v5
	v_cndmask_b32_e32 v8, v182, v8, vcc
	v_cmp_lt_f32_e64 vcc, |v7|, s18
	s_nop 1
	v_cndmask_b32_e32 v7, v8, v7, vcc
	v_add_f32_e32 v0, v0, v7
	v_mul_f32_e32 v80, 0xc138aa3b, v0
	v_ldexp_f32 v0, v10, v11
	v_cmp_ngt_f32_e64 vcc, |v4|, s77
	s_nop 1
	v_cndmask_b32_e32 v0, 0, v0, vcc
	v_cmp_nlt_f32_e64 vcc, |v4|, s58
	s_nop 1
	v_cndmask_b32_e32 v0, v182, v0, vcc
	v_add_f32_e32 v4, 1.0, v0
	v_add_f32_e32 v7, -1.0, v4
	v_sub_f32_e32 v8, v7, v4
	v_add_f32_e32 v8, 1.0, v8
	v_sub_f32_e32 v7, v0, v7
	v_add_f32_e32 v7, v7, v8
	v_frexp_mant_f32_e32 v10, v4
	v_cvt_f64_f32_e32 v[8:9], v4
	v_frexp_exp_i32_f64_e32 v8, v[8:9]
	v_cmp_gt_f32_e32 vcc, s5, v10
	s_nop 1
	v_subbrev_co_u32_e32 v8, vcc, 0, v8, vcc
	v_sub_u32_e32 v9, 0, v8
	v_ldexp_f32 v4, v4, v9
	v_ldexp_f32 v7, v7, v9
	v_add_f32_e32 v9, -1.0, v4
	v_add_f32_e32 v12, 1.0, v4
	v_add_f32_e32 v10, 1.0, v9
	v_add_f32_e32 v14, -1.0, v12
	v_sub_f32_e32 v10, v4, v10
	v_sub_f32_e32 v4, v4, v14
	v_add_f32_e32 v4, v7, v4
	v_add_f32_e32 v10, v7, v10
	v_add_f32_e32 v7, v12, v4
	v_rcp_f32_e32 v14, v7
	v_add_f32_e32 v11, v9, v10
	v_sub_f32_e32 v9, v9, v11
	v_add_f32_e32 v9, v10, v9
	v_sub_f32_e32 v10, v12, v7
	v_add_f32_e32 v4, v4, v10
	v_mul_f32_e32 v10, v11, v14
	v_mul_f32_e32 v12, v7, v10
	v_fma_f32 v15, v10, v7, -v12
	v_fmac_f32_e32 v15, v10, v4
	v_add_f32_e32 v16, v12, v15
	v_sub_f32_e32 v17, v11, v16
	v_sub_f32_e32 v11, v11, v17
	v_sub_f32_e32 v12, v16, v12
	v_sub_f32_e32 v11, v11, v16
	v_add_f32_e32 v9, v9, v11
	v_sub_f32_e32 v11, v12, v15
	v_add_f32_e32 v9, v11, v9
	v_add_f32_e32 v11, v17, v9
	v_mul_f32_e32 v12, v14, v11
	v_mul_f32_e32 v15, v7, v12
	v_fma_f32 v7, v12, v7, -v15
	v_fmac_f32_e32 v7, v12, v4
	v_sub_f32_e32 v4, v17, v11
	v_add_f32_e32 v4, v9, v4
	v_add_f32_e32 v9, v15, v7
	v_sub_f32_e32 v16, v11, v9
	v_sub_f32_e32 v11, v11, v16
	v_sub_f32_e32 v15, v9, v15
	v_sub_f32_e32 v9, v11, v9
	v_add_f32_e32 v4, v4, v9
	v_sub_f32_e32 v7, v15, v7
	v_cvt_f32_i32_e32 v8, v8
	v_add_f32_e32 v4, v7, v4
	v_add_f32_e32 v7, v10, v12
	v_add_f32_e32 v4, v16, v4
	v_sub_f32_e32 v9, v7, v10
	v_mul_f32_e32 v4, v14, v4
	v_sub_f32_e32 v9, v12, v9
	v_add_f32_e32 v4, v9, v4
	v_mul_f32_e32 v12, 0x3f317218, v8
	v_add_f32_e32 v9, v7, v4
	v_fma_f32 v14, v8, s19, -v12
	v_mul_f32_e32 v10, v9, v9
	v_fmac_f32_e32 v14, 0xb102e308, v8
	v_sub_f32_e32 v7, v9, v7
	v_fmamk_f32 v11, v10, 0x3e9b6dac, v171
	v_sub_f32_e32 v4, v4, v7
	v_add_f32_e32 v7, v12, v14
	v_fmaak_f32 v11, v10, v11, 0x3f2aaada
	v_sub_f32_e32 v8, v7, v12
	v_ldexp_f32 v12, v9, 1
	v_mul_f32_e32 v9, v9, v10
	v_mul_f32_e32 v9, v9, v11
	v_add_f32_e32 v10, v12, v9
	v_sub_f32_e32 v11, v10, v12
	v_ldexp_f32 v4, v4, 1
	v_sub_f32_e32 v9, v9, v11
	v_add_f32_e32 v4, v4, v9
	v_add_f32_e32 v9, v10, v4
	v_sub_f32_e32 v10, v9, v10
	v_sub_f32_e32 v4, v4, v10
	v_add_f32_e32 v10, v7, v9
	v_sub_f32_e32 v11, v10, v7
	v_sub_f32_e32 v12, v10, v11
	v_sub_f32_e32 v8, v14, v8
	v_sub_f32_e32 v7, v7, v12
	v_sub_f32_e32 v9, v9, v11
	v_add_f32_e32 v7, v9, v7
	v_add_f32_e32 v9, v8, v4
	v_sub_f32_e32 v11, v9, v8
	v_sub_f32_e32 v12, v9, v11
	v_sub_f32_e32 v8, v8, v12
	v_sub_f32_e32 v4, v4, v11
	v_add_f32_e32 v7, v9, v7
	v_add_f32_e32 v4, v4, v8
	v_add_f32_e32 v8, v10, v7
	v_sub_f32_e32 v9, v8, v10
	v_sub_f32_e32 v7, v7, v9
	v_add_f32_e32 v4, v4, v7
	v_add_f32_e32 v4, v8, v4
	v_cmp_neq_f32_e32 vcc, s4, v0
	s_nop 1
	v_cndmask_b32_e32 v4, v182, v4, vcc
	v_cmp_lt_f32_e64 vcc, |v0|, s18
	s_nop 1
	v_cndmask_b32_e32 v0, v4, v0, vcc
	v_mul_f32_e64 v4, |v6|, s59
	v_fma_f32 v7, |v6|, s59, -v4
	v_rndne_f32_e32 v8, v4
	v_fma_f32 v7, |v6|, s76, v7
	v_sub_f32_e32 v4, v4, v8
	v_add_f32_e32 v4, v4, v7
	v_exp_f32_e32 v4, v4
	v_cvt_i32_f32_e32 v7, v8
	v_cmp_ngt_f32_e64 vcc, |v6|, s77
	v_add_f32_e32 v0, v13, v0
	v_mul_f32_e32 v81, 0xc138aa3b, v0
	v_ldexp_f32 v4, v4, v7
	v_cndmask_b32_e32 v4, 0, v4, vcc
	v_cmp_nlt_f32_e64 vcc, |v6|, s58
	v_max_f32_e64 v0, -v6, -v6
	v_max_f32_e32 v0, 0, v0
	v_cndmask_b32_e32 v4, v182, v4, vcc
	v_add_f32_e32 v8, 1.0, v4
	v_add_f32_e32 v6, -1.0, v8
	v_sub_f32_e32 v7, v6, v8
	v_add_f32_e32 v7, 1.0, v7
	v_sub_f32_e32 v6, v4, v6
	v_add_f32_e32 v9, v6, v7
	v_frexp_mant_f32_e32 v10, v8
	v_cvt_f64_f32_e32 v[6:7], v8
	v_frexp_exp_i32_f64_e32 v6, v[6:7]
	v_cmp_gt_f32_e32 vcc, s5, v10
	s_nop 1
	v_subbrev_co_u32_e32 v6, vcc, 0, v6, vcc
	v_sub_u32_e32 v7, 0, v6
	v_ldexp_f32 v8, v8, v7
	v_ldexp_f32 v7, v9, v7
	v_add_f32_e32 v9, -1.0, v8
	v_add_f32_e32 v12, 1.0, v8
	v_add_f32_e32 v10, 1.0, v9
	v_add_f32_e32 v13, -1.0, v12
	v_sub_f32_e32 v10, v8, v10
	v_sub_f32_e32 v8, v8, v13
	v_add_f32_e32 v10, v7, v10
	v_add_f32_e32 v7, v7, v8
	v_add_f32_e32 v8, v12, v7
	v_rcp_f32_e32 v13, v8
	v_add_f32_e32 v11, v9, v10
	v_sub_f32_e32 v9, v9, v11
	v_add_f32_e32 v9, v10, v9
	v_sub_f32_e32 v10, v12, v8
	v_add_f32_e32 v7, v7, v10
	v_mul_f32_e32 v10, v11, v13
	v_mul_f32_e32 v12, v8, v10
	v_fma_f32 v14, v10, v8, -v12
	v_fmac_f32_e32 v14, v10, v7
	v_add_f32_e32 v15, v12, v14
	v_sub_f32_e32 v16, v11, v15
	v_sub_f32_e32 v11, v11, v16
	v_sub_f32_e32 v12, v15, v12
	v_sub_f32_e32 v11, v11, v15
	v_add_f32_e32 v9, v9, v11
	v_sub_f32_e32 v11, v12, v14
	v_add_f32_e32 v9, v11, v9
	v_add_f32_e32 v11, v16, v9
	v_mul_f32_e32 v12, v13, v11
	v_mul_f32_e32 v14, v8, v12
	v_fma_f32 v8, v12, v8, -v14
	v_fmac_f32_e32 v8, v12, v7
	v_sub_f32_e32 v7, v16, v11
	v_add_f32_e32 v7, v9, v7
	v_add_f32_e32 v9, v14, v8
	v_sub_f32_e32 v15, v11, v9
	v_sub_f32_e32 v11, v11, v15
	v_sub_f32_e32 v14, v9, v14
	v_sub_f32_e32 v9, v11, v9
	v_add_f32_e32 v7, v7, v9
	v_sub_f32_e32 v8, v14, v8
	v_cvt_f32_i32_e32 v6, v6
	v_add_f32_e32 v7, v8, v7
	v_add_f32_e32 v8, v10, v12
	v_add_f32_e32 v7, v15, v7
	v_sub_f32_e32 v9, v8, v10
; __device__ __forceinline__ float softplusf_(float x) { return fmaxf(x, 0.f) + log1pf(expf(-fabsf(x))); }
; __device__ __forceinline__ void lru_item(const Args& A, Frame& F, int l, int it) {
;     ...
;         spl[nt] = -8.f * 1.4426950408889634f * softplusf_(-GIN(18)[(size_t)(l * 2 + dir) * D + ch]);
;     }
;     const int c4 = (tid & 15) * 4, chg = blk * 64 + c4;
;     f32x4 cw[4];
; #pragma unroll
;     for (int j = 0; j < 4; ++j) cw[j] = *(const f32x4*)(GIN(14) + (size_t)(l * 4 + j) * D + chg);
;     const f32x4 cb = *(const f32x4*)(GIN(15) + (size_t)l * D + chg);
;     const bf16_t* lx = WSB(WS_LX) + (size_t)b * TB * D + chg;
;     bf16_t* hout = (dir ? WSB(WS_HB) : WSB(WS_HF)) + (size_t)b * TB * D + blk * 64;
;     __syncthreads();
;     const int g4 = tid >> 4;
;     u32x2 xr[7];
;     {
;         const int pb0 = dir == 0 ? 0 : 255;
;         const int pmin = dir == 0 ? pb0 + 4 * g4 : pb0 - 4 * g4 - 3;
; #pragma unroll
;         for (int e = 0; e < 7; ++e) { const int q = pmin - 2 + e; const int qc = q < 0 ? 0 : (q >= CTXL ? CTXL - 1 : q); xr[e] = *(const u32x2*)(lx + (size_t)qc * D); }
	v_mul_f32_e32 v7, v13, v7
	v_sub_f32_e32 v9, v12, v9
	v_add_f32_e32 v7, v9, v7
	v_mul_f32_e32 v12, 0x3f317218, v6
	v_add_f32_e32 v9, v8, v7
	v_fma_f32 v13, v6, s19, -v12
	v_mul_f32_e32 v10, v9, v9
	v_fmac_f32_e32 v13, 0xb102e308, v6
	v_sub_f32_e32 v6, v9, v8
	v_fmamk_f32 v11, v10, 0x3e9b6dac, v171
	v_sub_f32_e32 v6, v7, v6
	v_add_f32_e32 v7, v12, v13
	v_fmaak_f32 v11, v10, v11, 0x3f2aaada
	v_sub_f32_e32 v8, v7, v12
	v_ldexp_f32 v12, v9, 1
	v_mul_f32_e32 v9, v9, v10
	v_mul_f32_e32 v9, v9, v11
	v_add_f32_e32 v10, v12, v9
	v_sub_f32_e32 v11, v10, v12
	v_ldexp_f32 v6, v6, 1
	v_sub_f32_e32 v9, v9, v11
	v_add_f32_e32 v6, v6, v9
	v_add_f32_e32 v9, v10, v6
	v_sub_f32_e32 v10, v9, v10
	v_sub_f32_e32 v6, v6, v10
	v_add_f32_e32 v10, v7, v9
	v_sub_f32_e32 v11, v10, v7
	v_sub_f32_e32 v12, v10, v11
	v_sub_f32_e32 v8, v13, v8
	v_sub_f32_e32 v7, v7, v12
	v_sub_f32_e32 v9, v9, v11
	v_add_f32_e32 v7, v9, v7
	v_add_f32_e32 v9, v8, v6
	v_sub_f32_e32 v11, v9, v8
	v_sub_f32_e32 v12, v9, v11
	v_sub_f32_e32 v8, v8, v12
	v_sub_f32_e32 v6, v6, v11
	v_add_f32_e32 v7, v9, v7
	v_add_f32_e32 v6, v6, v8
	v_add_f32_e32 v8, v10, v7
	v_sub_f32_e32 v9, v8, v10
	v_sub_f32_e32 v7, v7, v9
	v_add_f32_e32 v6, v6, v7
	v_add_f32_e32 v6, v8, v6
	v_cmp_neq_f32_e32 vcc, s4, v4
	s_nop 1
	v_cndmask_b32_e32 v6, v182, v6, vcc
	v_cmp_lt_f32_e64 vcc, |v4|, s18
	s_mov_b32 s18, 0x3f2aaaab
	s_nop 0
	v_cndmask_b32_e32 v4, v6, v4, vcc
	v_add_f32_e32 v0, v0, v4
	v_mul_f32_e32 v82, 0xc138aa3b, v0
	v_mul_f32_e64 v0, |v5|, s59
	v_fma_f32 v4, |v5|, s59, -v0
	v_rndne_f32_e32 v6, v0
	v_fma_f32 v4, |v5|, s76, v4
	v_sub_f32_e32 v0, v0, v6
	v_add_f32_e32 v0, v0, v4
	v_exp_f32_e32 v0, v0
	v_cvt_i32_f32_e32 v4, v6
	v_cmp_ngt_f32_e64 vcc, |v5|, s77
	v_max_f32_e32 v6, 0, v2
	v_ldexp_f32 v0, v0, v4
	v_cndmask_b32_e32 v0, 0, v0, vcc
	v_cmp_nlt_f32_e64 vcc, |v5|, s58
	s_nop 1
	v_cndmask_b32_e32 v0, v182, v0, vcc
	v_add_f32_e32 v4, 1.0, v0
	v_add_f32_e32 v2, -1.0, v4
	v_sub_f32_e32 v3, v2, v4
	v_add_f32_e32 v3, 1.0, v3
	v_sub_f32_e32 v2, v0, v2
	v_add_f32_e32 v5, v2, v3
	v_frexp_mant_f32_e32 v7, v4
	v_cvt_f64_f32_e32 v[2:3], v4
	v_frexp_exp_i32_f64_e32 v2, v[2:3]
	v_cmp_gt_f32_e32 vcc, s5, v7
	s_nop 1
	v_subbrev_co_u32_e32 v2, vcc, 0, v2, vcc
	v_sub_u32_e32 v3, 0, v2
	v_ldexp_f32 v4, v4, v3
	v_ldexp_f32 v3, v5, v3
	v_add_f32_e32 v5, -1.0, v4
	v_add_f32_e32 v9, 1.0, v4
	v_add_f32_e32 v7, 1.0, v5
	v_add_f32_e32 v10, -1.0, v9
	v_sub_f32_e32 v7, v4, v7
	v_sub_f32_e32 v4, v4, v10
	v_add_f32_e32 v7, v3, v7
	v_add_f32_e32 v3, v3, v4
	v_add_f32_e32 v4, v9, v3
	v_rcp_f32_e32 v10, v4
	v_add_f32_e32 v8, v5, v7
	v_sub_f32_e32 v5, v5, v8
	v_add_f32_e32 v5, v7, v5
	v_sub_f32_e32 v7, v9, v4
	v_add_f32_e32 v3, v3, v7
	v_mul_f32_e32 v7, v8, v10
	v_mul_f32_e32 v9, v4, v7
	v_fma_f32 v11, v7, v4, -v9
	v_fmac_f32_e32 v11, v7, v3
	v_add_f32_e32 v12, v9, v11
	v_sub_f32_e32 v13, v8, v12
	v_sub_f32_e32 v8, v8, v13
	v_sub_f32_e32 v9, v12, v9
	v_sub_f32_e32 v8, v8, v12
	v_add_f32_e32 v5, v5, v8
	v_sub_f32_e32 v8, v9, v11
	v_add_f32_e32 v5, v8, v5
	v_add_f32_e32 v8, v13, v5
	v_mul_f32_e32 v9, v10, v8
	v_mul_f32_e32 v11, v4, v9
	v_fma_f32 v4, v9, v4, -v11
	v_fmac_f32_e32 v4, v9, v3
	v_sub_f32_e32 v3, v13, v8
	v_add_f32_e32 v3, v5, v3
	v_add_f32_e32 v5, v11, v4
	v_sub_f32_e32 v12, v8, v5
	v_sub_f32_e32 v8, v8, v12
	v_sub_f32_e32 v11, v5, v11
	v_sub_f32_e32 v5, v8, v5
	v_add_f32_e32 v3, v3, v5
	v_sub_f32_e32 v4, v11, v4
	v_cvt_f32_i32_e32 v2, v2
	v_add_f32_e32 v3, v4, v3
	v_add_f32_e32 v4, v7, v9
	v_add_f32_e32 v3, v12, v3
	v_sub_f32_e32 v5, v4, v7
	v_mul_f32_e32 v3, v10, v3
	v_sub_f32_e32 v5, v9, v5
	v_add_f32_e32 v3, v5, v3
	v_mul_f32_e32 v9, 0x3f317218, v2
	v_add_f32_e32 v5, v4, v3
	v_fma_f32 v10, v2, s19, -v9
	v_mul_f32_e32 v7, v5, v5
	v_fmac_f32_e32 v10, 0xb102e308, v2
	v_sub_f32_e32 v2, v5, v4
	v_fmamk_f32 v8, v7, 0x3e9b6dac, v171
	v_sub_f32_e32 v2, v3, v2
	v_add_f32_e32 v3, v9, v10
	v_fmaak_f32 v8, v7, v8, 0x3f2aaada
	v_sub_f32_e32 v4, v3, v9
	v_ldexp_f32 v9, v5, 1
	v_mul_f32_e32 v5, v5, v7
	v_mul_f32_e32 v5, v5, v8
	v_add_f32_e32 v7, v9, v5
	v_sub_f32_e32 v8, v7, v9
	v_ldexp_f32 v2, v2, 1
	v_sub_f32_e32 v5, v5, v8
	v_add_f32_e32 v2, v2, v5
	v_add_f32_e32 v5, v7, v2
	v_sub_f32_e32 v7, v5, v7
	v_sub_f32_e32 v2, v2, v7
	v_add_f32_e32 v7, v3, v5
	v_sub_f32_e32 v8, v7, v3
	v_sub_f32_e32 v9, v7, v8
	v_sub_f32_e32 v4, v10, v4
	v_sub_f32_e32 v3, v3, v9
	v_sub_f32_e32 v5, v5, v8
	v_add_f32_e32 v3, v5, v3
	v_add_f32_e32 v5, v4, v2
	v_sub_f32_e32 v8, v5, v4
	v_sub_f32_e32 v9, v5, v8
	v_sub_f32_e32 v4, v4, v9
	v_sub_f32_e32 v2, v2, v8
	v_add_f32_e32 v3, v5, v3
	v_add_f32_e32 v2, v2, v4
	v_add_f32_e32 v4, v7, v3
	v_sub_f32_e32 v5, v4, v7
	v_sub_f32_e32 v3, v3, v5
	v_add_f32_e32 v2, v2, v3
	v_add_f32_e32 v2, v4, v2
	v_cmp_neq_f32_e32 vcc, s4, v0
	v_readlane_b32 s4, v254, 38
	v_readlane_b32 s5, v254, 39
	v_cndmask_b32_e32 v2, v182, v2, vcc
	v_cmp_lt_f32_e64 vcc, |v0|, s12
	s_mov_b32 s19, 0x33800000
	v_cmp_eq_u32_e64 s[12:13], 7, v91
	v_cndmask_b32_e32 v0, v2, v0, vcc
	v_add_f32_e32 v0, v6, v0
	v_mul_f32_e32 v87, 0xc138aa3b, v0
	v_lshlrev_b32_e32 v0, 2, v54
	v_and_b32_e32 v23, 60, v0
	v_or_b32_e32 v24, s15, v23
	v_lshlrev_b32_e32 v0, 2, v24
	s_waitcnt lgkmcnt(0)
	v_lshl_add_u64 v[10:11], s[8:9], 0, v[0:1]
	v_lshl_add_u64 v[2:3], v[10:11], 0, s[4:5]
	s_add_u32 s4, s10, s74
	v_lshl_add_u64 v[6:7], v[10:11], 0, s[66:67]
	v_lshl_add_u64 v[12:13], v[10:11], 0, s[68:69]
	v_lshl_add_u64 v[14:15], v[10:11], 0, s[70:71]
	s_addc_u32 s5, s11, s75
	s_mul_hi_i32 s10, s14, 0x480000
	s_mul_i32 s14, s14, 0x480000
	global_load_dwordx4 v[2:5], v[2:3], off
	s_nop 0
	global_load_dwordx4 v[6:9], v[6:7], off
	s_nop 0
	global_load_dwordx4 v[10:13], v[12:13], off
	s_nop 0
	global_load_dwordx4 v[14:17], v[14:15], off
	v_lshl_add_u32 v89, v23, 2, 0
	global_load_dwordx4 v[18:21], v0, s[4:5]
	s_add_u32 s4, s42, s14
	s_addc_u32 s5, s43, s10
	v_lshlrev_b32_e32 v0, 1, v24
	s_cmp_eq_u32 s45, 0
	v_lshl_add_u64 v[56:57], s[4:5], 0, v[0:1]
	v_sub_u32_e32 v0, 0xfc, v88
	s_cselect_b64 s[8:9], -1, 0
	v_cndmask_b32_e64 v33, v0, v88, s[8:9]
	v_max_i32_e32 v0, 2, v33
	v_add_u32_e32 v0, -2, v0
	v_min_u32_e32 v0, 0xff, v0
	v_lshlrev_b32_e32 v0, 11, v0
	v_lshl_add_u64 v[24:25], v[56:57], 0, v[0:1]
	v_max_i32_e32 v0, 1, v33
	v_add_u32_e32 v0, -1, v0
	v_min_u32_e32 v0, 0xff, v0
	v_lshlrev_b32_e32 v0, 11, v0
	v_lshl_add_u64 v[26:27], v[56:57], 0, v[0:1]
	v_med3_i32 v0, v33, 0, v186
	v_lshlrev_b32_e32 v0, 11, v0
	v_lshl_add_u64 v[28:29], v[56:57], 0, v[0:1]
	v_or_b32_e32 v0, 1, v33
	v_med3_i32 v0, v0, 0, v186
	v_lshlrev_b32_e32 v0, 11, v0
	v_lshl_add_u64 v[30:31], v[56:57], 0, v[0:1]
	v_or_b32_e32 v0, 2, v33
	v_med3_i32 v0, v0, 0, v186
	v_lshlrev_b32_e32 v0, 11, v0
	s_barrier
; #define ST_LOAD(KS, VS, mc_) do { const int _p0 = 128 * (mc_); _Pragma("unroll") for (int ks = 0; ks < 4; ++ks) { VS[ks] = *(const bf16x8*)(vbase + _p0 + 32 * ks + 8 * fq); \
;         _Pragma("unroll") for (int t = 0; t < 2; ++t) KS[ks][t] = *(const bf16x8*)(kbase + (size_t)(16 * t) * TB + _p0 + 32 * ks + 8 * fq); } } while (0)
; __device__ __forceinline__ void ret_state_item(const Args& A, Frame& F, int l, int it) {
;     ...
;     ST_LOAD(ka, va, ST_MC(0));
; __device__ __forceinline__ void lru_item(const Args& A, Frame& F, int l, int it) {
;     ...
;         for (int e = 0; e < 7; ++e) { const int q = pmin - 2 + e; const int qc = q < 0 ? 0 : (q >= CTXL ? CTXL - 1 : q); xr[e] = *(const u32x2*)(lx + (size_t)qc * D); }
;     }
;     for (int sc = 0; sc < NCH; ++sc) {
;         const int lo = sc < 2 ? 0 : CTXL, hi = sc < 2 ? CTXL : TB;
;         const int pbase = dir == 0 ? 128 * sc : (sc < 2 ? 255 - 128 * sc : 2303 - 128 * (sc - 2));
	global_load_dwordx2 v[62:63], v[24:25], off
	global_load_dwordx2 v[64:65], v[26:27], off
	global_load_dwordx2 v[66:67], v[28:29], off
	global_load_dwordx2 v[68:69], v[30:31], off
	v_lshl_add_u64 v[24:25], v[56:57], 0, v[0:1]
	v_or_b32_e32 v0, 3, v33
	v_med3_i32 v0, v0, 0, v186
	v_lshlrev_b32_e32 v0, 11, v0
	v_lshl_add_u64 v[26:27], v[56:57], 0, v[0:1]
	v_max_i32_e32 v0, -4, v33
	v_add_u32_e32 v0, 4, v0
	v_min_u32_e32 v0, 0xff, v0
	v_lshlrev_b32_e32 v0, 11, v0
	v_lshl_add_u64 v[28:29], v[56:57], 0, v[0:1]
	global_load_dwordx2 v[70:71], v[24:25], off
	global_load_dwordx2 v[72:73], v[26:27], off
	global_load_dwordx2 v[74:75], v[28:29], off
	s_cmp_lg_u32 s45, 0
	s_cselect_b64 s[92:93], -1, 0
	s_and_b64 s[4:5], s[8:9], exec
	s_mov_b32 s4, 0x1d4c8000
	s_cselect_b32 s4, s4, 0x1f8c8000
	s_add_u32 s4, s30, s4
	s_addc_u32 s5, s31, 0
	s_add_u32 s4, s4, s14
	s_addc_u32 s5, s5, s10
	s_lshl_b32 s10, s39, 7
	s_add_u32 s4, s4, s10
	s_addc_u32 s5, s5, 0
	s_lshl_b32 s10, s26, 4
	v_or_b32_e32 v0, s10, v22
	v_mul_lo_u32 v0, v0, s97
	v_lshl_add_u32 v58, v23, 1, s21
	v_add_u32_e32 v23, s21, v0
	v_lshrrev_b32_e32 v0, 2, v54
	v_and_or_b32 v26, v0, 12, s10
	v_lshlrev_b32_e32 v0, 1, v102
	v_lshl_add_u64 v[60:61], s[4:5], 0, v[0:1]
	v_or_b32_e32 v0, 1, v88
	v_add_u32_e32 v29, -1, v90
	v_cndmask_b32_e64 v0, v29, v0, s[8:9]
	v_lshlrev_b32_e32 v29, 8, v0
	v_mul_lo_u32 v30, v0, s97
	v_or_b32_e32 v0, 2, v88
	v_add_u32_e32 v31, -2, v90
	v_lshlrev_b32_e32 v27, 2, v102
	v_cndmask_b32_e64 v0, v31, v0, s[8:9]
	v_lshlrev_b32_e32 v28, 4, v91
	v_lshlrev_b32_e32 v31, 8, v0
	v_mul_lo_u32 v32, v0, s97
	v_mul_u32_u24_e32 v33, 0x90, v22
	v_lshlrev_b32_e32 v0, 2, v22
	v_lshl_or_b32 v22, v91, 12, v27
	v_add_u32_e32 v96, 0, v22
	v_sub_u32_e32 v22, 0, v28
	v_cndmask_b32_e64 v97, v22, v28, s[8:9]
	v_or_b32_e32 v22, 1, v28
	v_lshl_or_b32 v0, v26, 8, v0
	v_lshl_or_b32 v26, v22, 8, v27
	v_add_u32_e32 v98, 0, v26
	v_sub_u32_e32 v26, 0, v22
	v_cndmask_b32_e64 v99, v26, v22, s[8:9]
	v_or_b32_e32 v22, 2, v28
	v_lshl_or_b32 v26, v22, 8, v27
	v_add_u32_e32 v100, 0, v26
	v_sub_u32_e32 v26, 0, v22
	v_cndmask_b32_e64 v101, v26, v22, s[8:9]
	v_or_b32_e32 v22, 3, v28
	v_lshl_or_b32 v26, v22, 8, v27
	v_add_u32_e32 v103, 0, v26
	v_sub_u32_e32 v26, 0, v22
	v_cndmask_b32_e64 v104, v26, v22, s[8:9]
	v_or_b32_e32 v22, 4, v28
	v_lshl_or_b32 v26, v22, 8, v27
	v_add_u32_e32 v105, 0, v26
	v_sub_u32_e32 v26, 0, v22
	v_cndmask_b32_e64 v106, v26, v22, s[8:9]
	v_or_b32_e32 v22, 5, v28
	v_lshl_or_b32 v26, v22, 8, v27
	v_add_u32_e32 v107, 0, v26
	v_sub_u32_e32 v26, 0, v22
	v_cndmask_b32_e64 v108, v26, v22, s[8:9]
	v_or_b32_e32 v22, 6, v28
	v_lshl_or_b32 v26, v22, 8, v27
	v_add_u32_e32 v109, 0, v26
	v_sub_u32_e32 v26, 0, v22
	v_cndmask_b32_e64 v110, v26, v22, s[8:9]
	v_or_b32_e32 v22, 7, v28
	v_lshl_or_b32 v26, v22, 8, v27
	v_add_u32_e32 v111, 0, v26
	v_sub_u32_e32 v26, 0, v22
	v_cndmask_b32_e64 v112, v26, v22, s[8:9]
	v_or_b32_e32 v22, 8, v28
	v_lshl_or_b32 v26, v22, 8, v27
	v_add_u32_e32 v113, 0, v26
	v_sub_u32_e32 v26, 0, v22
	v_cndmask_b32_e64 v114, v26, v22, s[8:9]
	v_or_b32_e32 v22, 9, v28
	v_lshl_or_b32 v26, v22, 8, v27
	v_add_u32_e32 v115, 0, v26
	v_sub_u32_e32 v26, 0, v22
	v_cndmask_b32_e64 v116, v26, v22, s[8:9]
	v_or_b32_e32 v22, 10, v28
	v_lshl_or_b32 v26, v22, 8, v27
	v_add_u32_e32 v117, 0, v26
	v_sub_u32_e32 v26, 0, v22
	v_cndmask_b32_e64 v118, v26, v22, s[8:9]
	v_or_b32_e32 v22, 11, v28
	v_lshl_or_b32 v26, v22, 8, v27
	v_add_u32_e32 v119, 0, v26
	v_sub_u32_e32 v26, 0, v22
	v_cndmask_b32_e64 v120, v26, v22, s[8:9]
	v_or_b32_e32 v22, 12, v28
	v_lshl_or_b32 v26, v22, 8, v27
	v_add_u32_e32 v121, 0, v26
	v_sub_u32_e32 v26, 0, v22
	v_cndmask_b32_e64 v122, v26, v22, s[8:9]
	v_or_b32_e32 v22, 13, v28
	v_lshl_or_b32 v26, v22, 8, v27
	v_add_u32_e32 v123, 0, v26
	v_sub_u32_e32 v26, 0, v22
	v_cndmask_b32_e64 v124, v26, v22, s[8:9]
	v_or_b32_e32 v22, 14, v28
	v_lshl_or_b32 v26, v22, 8, v27
	v_add_u32_e32 v125, 0, v26
	v_sub_u32_e32 v26, 0, v22
	v_cndmask_b32_e64 v126, v26, v22, s[8:9]
	v_or_b32_e32 v22, 15, v28
	v_and_b32_e32 v24, 48, v54
	v_lshl_or_b32 v26, v22, 8, v27
	v_add_u32_e32 v25, s17, v24
	s_add_i32 s10, 0, 0x1b000
	v_add_u32_e32 v0, 0, v0
	v_add_u32_e32 v127, 0, v26
	v_sub_u32_e32 v26, 0, v22
	v_readlane_b32 s4, v254, 13
	v_add_u32_e32 v92, s10, v27
	v_cmp_lt_i32_e64 s[10:11], 0, v91
	v_add_u32_e32 v93, 64, v0
	v_add_u32_e32 v94, 0x80, v0
	v_add_u32_e32 v95, 0xc0, v0
	v_cndmask_b32_e64 v128, v26, v22, s[8:9]
	v_add_u32_e32 v129, s4, v27
	v_add_u32_e32 v130, v89, v29
	v_add_u32_e32 v131, v58, v30
	v_add_u32_e32 v132, v89, v31
	v_add_u32_e32 v133, v58, v32
	v_add_u32_e32 v134, v23, v24
	v_add_u32_e32 v135, v25, v33
	s_waitcnt vmcnt(0)
	s_mov_b32 s100, 0
	s_bfe_u32 s101, s37, 0x10001
	s_cmp_eq_u32 s101, 0
	s_cbranch_scc1 .Lfz_mc_pre
	s_sub_i32 s101, 19, s100
	s_cmp_lt_u32 s100, 2
	s_cbranch_scc0 .Lfz_mc1_pre
	s_sub_i32 s101, 1, s100
.Lfz_mc1_pre:
	s_mov_b32 s100, s101
.Lfz_mc_pre:
	s_lshl_b32 s101, s100, 8
	s_add_u32 s98, s30, 0xd8c8000
	s_addc_u32 s99, s31, 0
	s_add_u32 s98, s98, s101
	s_addc_u32 s99, s99, 0
	global_load_dwordx4 v[190:193], v242, s[98:99]
	global_load_dwordx4 v[194:197], v242, s[98:99] offset:64
	global_load_dwordx4 v[198:201], v242, s[98:99] offset:128
	global_load_dwordx4 v[202:205], v242, s[98:99] offset:192
	s_sub_u32 s98, s98, 0x1200000
	s_subb_u32 s99, s99, 0
	global_load_dwordx4 v[206:209], v169, s[98:99]
	global_load_dwordx4 v[214:217], v169, s[98:99] offset:64
	global_load_dwordx4 v[222:225], v169, s[98:99] offset:128
	global_load_dwordx4 v[230:233], v169, s[98:99] offset:192
	s_add_u32 s98, s98, 0x12000
	s_addc_u32 s99, s99, 0
	global_load_dwordx4 v[210:213], v169, s[98:99]
	global_load_dwordx4 v[218:221], v169, s[98:99] offset:64
	global_load_dwordx4 v[226:229], v169, s[98:99] offset:128
	global_load_dwordx4 v[234:237], v169, s[98:99] offset:192
	s_branch .LBB0_63

; #define LAS __attribute__((address_space(3)))
; __device__ __forceinline__ unsigned pk2(float lo, float hi) { const f32x2_t v = {lo, hi}; const bf16v2_t b = __builtin_convertvector(v, bf16v2_t); return __builtin_bit_cast(unsigned, b); }
; __device__ __forceinline__ float bflo(unsigned u) { return __uint_as_float(u << 16); }
; __device__ __forceinline__ float bfhi(unsigned u) { return __uint_as_float(u & 0xffff0000u); }
; __device__ __forceinline__ void lru_item(const Args& A, Frame& F, int l, int it) {
;     ...
;         const int lo = sc < 2 ? 0 : CTXL, hi = sc < 2 ? CTXL : TB;
;         const int pbase = dir == 0 ? 128 * sc : (sc < 2 ? 255 - 128 * sc : 2303 - 128 * (sc - 2));
;         {
;             const int pmin = dir == 0 ? pbase + 4 * g4 : pbase - 4 * g4 - 3;
;             f32x4 xw[7];
; #pragma unroll
;             for (int e = 0; e < 7; ++e) {
;                 const int q = pmin - 2 + e;
;                 const float msk = (q >= lo && q < hi) ? 1.f : 0.f;
;                 xw[e][0] = bflo(xr[e].x) * msk; xw[e][1] = bfhi(xr[e].x) * msk; xw[e][2] = bflo(xr[e].y) * msk; xw[e][3] = bfhi(xr[e].y) * msk;
;             }
; #pragma unroll
;             for (int m = 0; m < 4; ++m) {
;                 const f32x4 a = cb + cw[0] * xw[m] + cw[1] * xw[m + 1] + cw[2] * xw[m + 2] + cw[3] * xw[m + 3];
;                 const int si = dir == 0 ? 4 * g4 + m : 4 * g4 + 3 - m;
;                 *(LAS f32x4*)(us + si * 64 + c4) = a;
;                 u32x2 o; o.x = pk2(a[0], a[1]); o.y = pk2(a[2], a[3]);
;                 *(LAS u32x2*)(ub + si * 72 + c4) = o;
;             }
;         }
.LBB0_70:
	v_sub_u32_e32 v24, s39, v88
	s_and_b64 s[4:5], s[4:5], exec
	v_add_u32_e32 v23, s39, v88
	v_add_u32_e32 v24, -3, v24
	s_movk_i32 s4, 0x100
	v_cndmask_b32_e64 v23, v24, v23, s[8:9]
	s_cselect_b32 s25, 0, 0x100
	s_cselect_b32 s52, s4, 0x900
	v_add_u32_e32 v24, -2, v23
	v_cmp_le_i32_e32 vcc, s25, v24
	v_cmp_gt_i32_e64 s[14:15], s52, v24
	s_and_b64 s[4:5], vcc, s[14:15]
	v_cmp_lt_i32_e32 vcc, s25, v23
	v_cmp_ge_i32_e64 s[14:15], s52, v23
	v_cndmask_b32_e64 v24, 0, 1.0, s[4:5]
	s_waitcnt vmcnt(36)
	v_lshlrev_b32_e32 v26, 16, v62
	v_and_b32_e32 v27, 0xffff0000, v62
	v_lshlrev_b32_e32 v28, 16, v63
	v_and_b32_e32 v29, 0xffff0000, v63
	s_and_b64 s[4:5], vcc, s[14:15]
	v_cmp_le_i32_e32 vcc, s25, v23
	v_cmp_gt_i32_e64 s[14:15], s52, v23
	v_pk_mul_f32 v[26:27], v[24:25], v[26:27] op_sel_hi:[0,1]
	v_pk_mul_f32 v[24:25], v[24:25], v[28:29] op_sel_hi:[0,1]
	v_cndmask_b32_e64 v28, 0, 1.0, s[4:5]
	s_waitcnt vmcnt(35)
	v_lshlrev_b32_e32 v30, 16, v64
	v_and_b32_e32 v31, 0xffff0000, v64
	v_lshlrev_b32_e32 v32, 16, v65
	v_and_b32_e32 v33, 0xffff0000, v65
	s_and_b64 s[4:5], vcc, s[14:15]
	v_pk_mul_f32 v[30:31], v[28:29], v[30:31] op_sel_hi:[0,1]
	v_pk_mul_f32 v[28:29], v[28:29], v[32:33] op_sel_hi:[0,1]
	v_cndmask_b32_e64 v32, 0, 1.0, s[4:5]
	s_waitcnt vmcnt(34)
	v_lshlrev_b32_e32 v34, 16, v66
	v_and_b32_e32 v35, 0xffff0000, v66
	v_lshlrev_b32_e32 v36, 16, v67
	v_and_b32_e32 v37, 0xffff0000, v67
	v_pk_mul_f32 v[34:35], v[32:33], v[34:35] op_sel_hi:[0,1]
	v_pk_mul_f32 v[32:33], v[32:33], v[36:37] op_sel_hi:[0,1]
	v_add_u32_e32 v36, 1, v23
	v_cmp_le_i32_e32 vcc, s25, v36
	v_cmp_gt_i32_e64 s[14:15], s52, v36
	s_and_b64 s[4:5], vcc, s[14:15]
	v_cndmask_b32_e64 v36, 0, 1.0, s[4:5]
	s_waitcnt vmcnt(33)
	v_lshlrev_b32_e32 v38, 16, v68
	v_and_b32_e32 v39, 0xffff0000, v68
	v_lshlrev_b32_e32 v40, 16, v69
	v_and_b32_e32 v41, 0xffff0000, v69
	v_pk_mul_f32 v[38:39], v[36:37], v[38:39] op_sel_hi:[0,1]
	v_pk_mul_f32 v[36:37], v[36:37], v[40:41] op_sel_hi:[0,1]
	v_add_u32_e32 v40, 2, v23
	v_cmp_le_i32_e32 vcc, s25, v40
	v_cmp_gt_i32_e64 s[14:15], s52, v40
	s_and_b64 s[4:5], vcc, s[14:15]
	v_cndmask_b32_e64 v40, 0, 1.0, s[4:5]
	s_waitcnt vmcnt(32)
	v_lshlrev_b32_e32 v42, 16, v70
	v_and_b32_e32 v43, 0xffff0000, v70
	v_lshlrev_b32_e32 v44, 16, v71
	v_and_b32_e32 v45, 0xffff0000, v71
	v_pk_mul_f32 v[42:43], v[40:41], v[42:43] op_sel_hi:[0,1]
	v_pk_mul_f32 v[40:41], v[40:41], v[44:45] op_sel_hi:[0,1]
	v_add_u32_e32 v44, 3, v23
	v_cmp_le_i32_e32 vcc, s25, v44
	v_cmp_gt_i32_e64 s[14:15], s52, v44
	v_add_u32_e32 v23, 4, v23
	s_and_b64 s[4:5], vcc, s[14:15]
	v_cmp_le_i32_e32 vcc, s25, v23
	v_cmp_gt_i32_e64 s[14:15], s52, v23
	v_cndmask_b32_e64 v44, 0, 1.0, s[4:5]
	s_waitcnt vmcnt(31)
	v_lshlrev_b32_e32 v46, 16, v72
	v_and_b32_e32 v47, 0xffff0000, v72
	v_lshlrev_b32_e32 v48, 16, v73
	v_and_b32_e32 v49, 0xffff0000, v73
	s_and_b64 s[4:5], vcc, s[14:15]
	v_pk_fma_f32 v[26:27], v[2:3], v[26:27], v[18:19]
	v_pk_fma_f32 v[24:25], v[4:5], v[24:25], v[20:21]
	v_pk_mul_f32 v[46:47], v[44:45], v[46:47] op_sel_hi:[0,1]
	v_pk_mul_f32 v[44:45], v[44:45], v[48:49] op_sel_hi:[0,1]
	v_cndmask_b32_e64 v48, 0, 1.0, s[4:5]
	s_waitcnt vmcnt(30)
	v_lshlrev_b32_e32 v50, 16, v74
	v_and_b32_e32 v51, 0xffff0000, v74
	v_lshlrev_b32_e32 v52, 16, v75
	v_and_b32_e32 v53, 0xffff0000, v75
	v_pk_fma_f32 v[24:25], v[8:9], v[28:29], v[24:25]
	v_pk_fma_f32 v[26:27], v[6:7], v[30:31], v[26:27]
	v_pk_mul_f32 v[50:51], v[48:49], v[50:51] op_sel_hi:[0,1]
	v_pk_mul_f32 v[48:49], v[48:49], v[52:53] op_sel_hi:[0,1]
	v_pk_fma_f32 v[52:53], v[10:11], v[34:35], v[26:27]
	v_pk_fma_f32 v[24:25], v[12:13], v[32:33], v[24:25]
	v_lshl_add_u32 v23, v22, 8, v89
	v_pk_fma_f32 v[26:27], v[16:17], v[36:37], v[24:25]
	v_pk_fma_f32 v[24:25], v[14:15], v[38:39], v[52:53]
	ds_write_b128 v23, v[24:27]
	v_cvt_pk_bf16_f32 v24, v24, v25
	v_cvt_pk_bf16_f32 v25, v26, v27
	v_mad_u64_u32 v[22:23], s[4:5], v22, s97, v[58:59]
	ds_write_b64 v22, v[24:25]
	v_pk_fma_f32 v[22:23], v[2:3], v[30:31], v[18:19]
	v_pk_fma_f32 v[24:25], v[4:5], v[28:29], v[20:21]
	v_pk_fma_f32 v[22:23], v[6:7], v[34:35], v[22:23]
	v_pk_fma_f32 v[24:25], v[8:9], v[32:33], v[24:25]
	v_pk_fma_f32 v[22:23], v[10:11], v[38:39], v[22:23]
	v_pk_fma_f32 v[24:25], v[12:13], v[36:37], v[24:25]
	v_pk_fma_f32 v[22:23], v[14:15], v[42:43], v[22:23]
	v_pk_fma_f32 v[24:25], v[16:17], v[40:41], v[24:25]
	ds_write_b128 v130, v[22:25]
	v_cvt_pk_bf16_f32 v22, v22, v23
	v_cvt_pk_bf16_f32 v23, v24, v25
	ds_write_b64 v131, v[22:23]
	v_pk_fma_f32 v[22:23], v[2:3], v[34:35], v[18:19]
	v_pk_fma_f32 v[24:25], v[4:5], v[32:33], v[20:21]
	v_pk_fma_f32 v[22:23], v[6:7], v[38:39], v[22:23]
	v_pk_fma_f32 v[24:25], v[8:9], v[36:37], v[24:25]
	v_pk_fma_f32 v[22:23], v[10:11], v[42:43], v[22:23]
	v_pk_fma_f32 v[24:25], v[12:13], v[40:41], v[24:25]
	v_pk_fma_f32 v[22:23], v[14:15], v[46:47], v[22:23]
	v_pk_fma_f32 v[24:25], v[16:17], v[44:45], v[24:25]
	ds_write_b128 v132, v[22:25]
	v_cvt_pk_bf16_f32 v22, v22, v23
	v_cvt_pk_bf16_f32 v23, v24, v25
	ds_write_b64 v133, v[22:23]
	v_pk_fma_f32 v[22:23], v[2:3], v[38:39], v[18:19]
	v_pk_fma_f32 v[24:25], v[4:5], v[36:37], v[20:21]
	v_pk_fma_f32 v[22:23], v[6:7], v[42:43], v[22:23]
	v_pk_fma_f32 v[24:25], v[8:9], v[40:41], v[24:25]
	v_pk_fma_f32 v[22:23], v[10:11], v[46:47], v[22:23]
	v_pk_fma_f32 v[24:25], v[12:13], v[44:45], v[24:25]
	v_or_b32_e32 v26, s45, v88
	v_pk_fma_f32 v[24:25], v[16:17], v[48:49], v[24:25]
	v_pk_fma_f32 v[22:23], v[14:15], v[50:51], v[22:23]
	v_lshl_add_u32 v27, v26, 8, v89
	s_add_i32 s45, s2, 1
	ds_write_b128 v27, v[22:25]
	v_cvt_pk_bf16_f32 v22, v22, v23
	v_cvt_pk_bf16_f32 v23, v24, v25
	v_mad_u64_u32 v[24:25], s[4:5], v26, s97, v[58:59]
; #define LAS __attribute__((address_space(3)))
; __device__ __forceinline__ void lru_item(const Args& A, Frame& F, int l, int it) {
;     ...
;             const int sn = sc + 1 < NCH ? sc + 1 : sc;
;             const int lon = sn < 2 ? 0 : CTXL, hin = sn < 2 ? CTXL : TB;
;             const int pbn = dir == 0 ? 128 * sn : (sn < 2 ? 255 - 128 * sn : 2303 - 128 * (sn - 2));
;             const int pminn = dir == 0 ? pbn + 4 * g4 : pbn - 4 * g4 - 3;
; #pragma unroll
;             for (int e = 0; e < 7; ++e) { const int q = pminn - 2 + e; const int qc = q < lon ? lon : (q >= hin ? hin - 1 : q); xr[e] = *(const u32x2*)(lx + (size_t)qc * D); }
;         }
;         __builtin_amdgcn_fence(__ATOMIC_RELEASE, "workgroup"); __builtin_amdgcn_wave_barrier(); __builtin_amdgcn_fence(__ATOMIC_ACQUIRE, "workgroup");
;         {
;             bf16x8 af[2];
; #pragma unroll
;             for (int ks = 0; ks < 2; ++ks) af[ks] = *(const LAS bf16x8*)(ub + (16 * w + fr) * 72 + 32 * ks + 8 * fq);
;             f32x4 gacc[8];
; #pragma unroll
;             for (int nt = 0; nt < 8; ++nt) {
;                 gacc[nt] = (f32x4){0.f, 0.f, 0.f, 0.f};
; #pragma unroll
;                 for (int ks = 0; ks < 2; ++ks) {
;                     const bf16x8 bfm = *(const LAS bf16x8*)(wgs + (16 * nt + fr) * 72 + 32 * ks + 8 * fq);
;                     gacc[nt] = __builtin_amdgcn_mfma_f32_16x16x32_bf16(af[ks], bfm, gacc[nt], 0, 0, 0);
;                 }
;             }
; #pragma unroll
;             for (int nt = 0; nt < 4; ++nt)
; #pragma unroll
;                 for (int r = 0; r < 4; ++r) {
;                     const int si = 16 * w + 4 * fq + r, ch = 16 * nt + fr;
;                     const float d0 = 1.f + __builtin_amdgcn_exp2f(fminf((gacc[nt][r] + bgr[nt]) * -1.4426950408889634f, 60.f));
;                     const float d1 = 1.f + __builtin_amdgcn_exp2f(fminf((gacc[nt + 4][r] + bgi[nt]) * -1.4426950408889634f, 60.f));
;                     const float rr = frcp(d0 * d1);
;                     const float rg = rr * d1, ig = rr * d0;
;                     const float av = __builtin_amdgcn_exp2f(rg * spl[nt]);
;                     const float mult = __builtin_amdgcn_sqrtf(fmaxf(1.f - av * av, 0.f));
;                     const float uu = us[si * 64 + ch];
;                     as[si * 64 + ch] = av;
;                     us[si * 64 + ch] = mult * ig * uu;
	s_cmp_lg_u32 s2, 17
	s_cselect_b32 s4, s45, 17
	s_lshl_b32 s14, s4, 7
	s_sub_i32 s5, 0x9ff, s14
	s_cmp_lt_u32 s4, 2
	s_movk_i32 s4, 0x8ff
	s_cselect_b32 s15, 0, 0x100
	s_cselect_b32 s25, 0x7f, s5
	s_cselect_b32 s52, 0xff, s4
	s_and_b64 s[4:5], s[8:9], exec
	s_cselect_b32 s4, s14, s25
	ds_write_b64 v24, v[22:23]
	v_sub_u32_e32 v23, s4, v88
	v_add_u32_e32 v22, s14, v88
	v_add_u32_e32 v23, -3, v23
	v_cndmask_b32_e64 v24, v23, v22, s[8:9]
	v_add_u32_e32 v22, -2, v24
	v_cmp_gt_i32_e32 vcc, s15, v22
	v_min_i32_e32 v22, s52, v22
	v_mov_b32_e32 v25, s15
	v_cndmask_b32_e32 v22, v22, v25, vcc
	v_ashrrev_i32_e32 v23, 31, v22
	v_lshlrev_b64 v[22:23], 11, v[22:23]
	v_lshl_add_u64 v[22:23], v[56:57], 0, v[22:23]
	global_load_dwordx2 v[62:63], v[22:23], off
	v_add_u32_e32 v22, -1, v24
	v_cmp_lt_i32_e32 vcc, s15, v24
	v_min_i32_e32 v22, s52, v22
	s_and_b32 s2, s2, 1
	v_cndmask_b32_e32 v22, v25, v22, vcc
	v_ashrrev_i32_e32 v23, 31, v22
	v_lshlrev_b64 v[22:23], 11, v[22:23]
	v_lshl_add_u64 v[22:23], v[56:57], 0, v[22:23]
	global_load_dwordx2 v[64:65], v[22:23], off
	v_cmp_gt_i32_e32 vcc, s15, v24
	v_min_i32_e32 v22, s52, v24
	s_lshl_b32 s4, s2, 12
	v_cndmask_b32_e32 v22, v22, v25, vcc
	v_ashrrev_i32_e32 v23, 31, v22
	v_lshlrev_b64 v[22:23], 11, v[22:23]
	v_lshl_add_u64 v[22:23], v[56:57], 0, v[22:23]
	global_load_dwordx2 v[66:67], v[22:23], off
	v_add_u32_e32 v22, 1, v24
	v_cmp_gt_i32_e32 vcc, s15, v22
	v_min_i32_e32 v22, s52, v22
	s_add_i32 s4, s4, 0
	v_cndmask_b32_e32 v22, v22, v25, vcc
	v_ashrrev_i32_e32 v23, 31, v22
	v_lshlrev_b64 v[22:23], 11, v[22:23]
	v_lshl_add_u64 v[22:23], v[56:57], 0, v[22:23]
	global_load_dwordx2 v[68:69], v[22:23], off
	v_add_u32_e32 v22, 2, v24
	v_cmp_gt_i32_e32 vcc, s15, v22
	v_min_i32_e32 v22, s52, v22
	s_nop 0
	v_cndmask_b32_e32 v22, v22, v25, vcc
	v_ashrrev_i32_e32 v23, 31, v22
	v_lshlrev_b64 v[22:23], 11, v[22:23]
	v_lshl_add_u64 v[22:23], v[56:57], 0, v[22:23]
	global_load_dwordx2 v[70:71], v[22:23], off
	v_add_u32_e32 v22, 3, v24
	v_cmp_gt_i32_e32 vcc, s15, v22
	v_min_i32_e32 v22, s52, v22
	s_nop 0
	v_cndmask_b32_e32 v22, v22, v25, vcc
	v_ashrrev_i32_e32 v23, 31, v22
	v_lshlrev_b64 v[22:23], 11, v[22:23]
	v_lshl_add_u64 v[22:23], v[56:57], 0, v[22:23]
	global_load_dwordx2 v[72:73], v[22:23], off
	v_add_u32_e32 v22, 4, v24
	v_cmp_gt_i32_e32 vcc, s15, v22
	v_min_i32_e32 v22, s52, v22
	s_nop 0
	v_cndmask_b32_e32 v22, v22, v25, vcc
	v_ashrrev_i32_e32 v23, 31, v22
	v_lshlrev_b64 v[22:23], 11, v[22:23]
	v_lshl_add_u64 v[22:23], v[56:57], 0, v[22:23]
	global_load_dwordx2 v[74:75], v[22:23], off
	s_waitcnt lgkmcnt(0)
	ds_read_b128 v[26:29], v134
	ds_read_b128 v[144:147], v134 offset:64
	ds_read_b128 v[22:25], v135
	ds_read_b128 v[30:33], v135 offset:64
	ds_read_b128 v[34:37], v135 offset:6976
	s_waitcnt lgkmcnt(2)
	v_mfma_f32_16x16x32_bf16 v[22:25], v[26:29], v[22:25], 0
	ds_read_b128 v[42:45], v135 offset:9280
	ds_read_b128 v[148:151], v135 offset:13888
	s_waitcnt lgkmcnt(3)
	v_mfma_f32_16x16x32_bf16 v[46:49], v[144:147], v[30:33], v[22:25]
	ds_read_b128 v[30:33], v135 offset:2368
	s_nop 2
	ds_read_b128 v[22:25], v135 offset:2304
	s_waitcnt lgkmcnt(0)
	v_mfma_f32_16x16x32_bf16 v[22:25], v[26:29], v[22:25], 0
	s_nop 0
	v_add_f32_e32 v46, v55, v46
	v_mul_f32_e32 v46, 0xbfb8aa3b, v46
	v_min_f32_e32 v46, 0x42700000, v46
	v_mfma_f32_16x16x32_bf16 v[38:41], v[144:147], v[30:33], v[22:25]
	ds_read_b128 v[30:33], v135 offset:4672
	v_exp_f32_e32 v46, v46
	v_add_f32_e32 v48, v55, v48
	ds_read_b128 v[22:25], v135 offset:4608
	s_waitcnt lgkmcnt(0)
	v_mfma_f32_16x16x32_bf16 v[22:25], v[26:29], v[22:25], 0
	v_add_f32_e32 v46, 1.0, v46
	v_mul_f32_e32 v48, 0xbfb8aa3b, v48
	v_min_f32_e32 v48, 0x42700000, v48
	v_mfma_f32_16x16x32_bf16 v[30:33], v[144:147], v[30:33], v[22:25]
	v_exp_f32_e32 v48, v48
	v_add_f32_e32 v38, v59, v38
	v_mul_f32_e32 v38, 0xbfb8aa3b, v38
	s_nop 0
	ds_read_b128 v[22:25], v135 offset:6912
	s_waitcnt lgkmcnt(0)
	v_mfma_f32_16x16x32_bf16 v[22:25], v[26:29], v[22:25], 0
	v_add_f32_e32 v48, 1.0, v48
	v_min_f32_e32 v38, 0x42700000, v38
	v_exp_f32_e32 v38, v38
	v_mfma_f32_16x16x32_bf16 v[22:25], v[144:147], v[34:37], v[22:25]
	ds_read_b128 v[34:37], v135 offset:9216
	v_add_f32_e32 v40, v59, v40
	v_add_f32_e32 v38, 1.0, v38
	s_waitcnt lgkmcnt(0)
	v_mfma_f32_16x16x32_bf16 v[34:37], v[26:29], v[34:37], 0
	v_mul_f32_e32 v40, 0xbfb8aa3b, v40
	v_min_f32_e32 v40, 0x42700000, v40
	v_exp_f32_e32 v40, v40
	v_mfma_f32_16x16x32_bf16 v[50:53], v[144:147], v[42:45], v[34:37]
	ds_read_b128 v[42:45], v135 offset:11584
	v_add_f32_e32 v30, v78, v30
	v_add_f32_e32 v40, 1.0, v40
	s_nop 0
	ds_read_b128 v[34:37], v135 offset:11520
	s_waitcnt lgkmcnt(0)
	v_mfma_f32_16x16x32_bf16 v[34:37], v[26:29], v[34:37], 0
	s_nop 0
	v_add_f32_e32 v50, v83, v50
	v_mul_f32_e32 v50, 0xbfb8aa3b, v50
	v_min_f32_e32 v50, 0x42700000, v50
	v_exp_f32_e32 v50, v50
	v_mfma_f32_16x16x32_bf16 v[42:45], v[144:147], v[42:45], v[34:37]
	v_mul_f32_e32 v30, 0xbfb8aa3b, v30
	v_min_f32_e32 v30, 0x42700000, v30
	v_add_f32_e32 v50, 1.0, v50
	v_mul_f32_e32 v76, v46, v50
	v_rcp_f32_e32 v76, v76
	ds_read_b128 v[34:37], v135 offset:13824
	s_waitcnt lgkmcnt(0)
	v_mfma_f32_16x16x32_bf16 v[34:37], v[26:29], v[34:37], 0
	v_mul_f32_e32 v50, v50, v76
	v_mul_f32_e32 v50, v80, v50
	v_exp_f32_e32 v50, v50
	v_mul_f32_e32 v46, v46, v76
	v_mfma_f32_16x16x32_bf16 v[34:37], v[144:147], v[148:151], v[34:37]
	ds_read_b128 v[148:151], v135 offset:16128
	v_fma_f32 v76, -v50, v50, 1.0
	v_max_f32_e32 v76, 0, v76
	v_sqrt_f32_e32 v136, v76
	ds_read2_b32 v[76:77], v0 offset1:16
	s_waitcnt lgkmcnt(1)
	v_mfma_f32_16x16x32_bf16 v[26:29], v[26:29], v[148:151], 0
	ds_read_b128 v[148:151], v135 offset:16192
	v_mul_f32_e32 v46, v46, v136
	ds_write_b32 v0, v50 offset:32768
	s_waitcnt lgkmcnt(2)
; __device__ __forceinline__ float frcp(float x) { return __builtin_amdgcn_rcpf(x); }
; __device__ __forceinline__ void lru_item(const Args& A, Frame& F, int l, int it) {
;     ...
;             for (int nt = 0; nt < 4; ++nt)
; #pragma unroll
;                 for (int r = 0; r < 4; ++r) {
;                     const int si = 16 * w + 4 * fq + r, ch = 16 * nt + fr;
;                     const float d0 = 1.f + __builtin_amdgcn_exp2f(fminf((gacc[nt][r] + bgr[nt]) * -1.4426950408889634f, 60.f));
;                     const float d1 = 1.f + __builtin_amdgcn_exp2f(fminf((gacc[nt + 4][r] + bgi[nt]) * -1.4426950408889634f, 60.f));
;                     const float rr = frcp(d0 * d1);
;                     const float rg = rr * d1, ig = rr * d0;
;                     const float av = __builtin_amdgcn_exp2f(rg * spl[nt]);
;                     const float mult = __builtin_amdgcn_sqrtf(fmaxf(1.f - av * av, 0.f));
;                     const float uu = us[si * 64 + ch];
;                     as[si * 64 + ch] = av;
;                     us[si * 64 + ch] = mult * ig * uu;
;                 }
	v_mul_f32_e32 v46, v76, v46
	ds_write_b32 v0, v46
	v_add_f32_e32 v46, v55, v47
	v_add_f32_e32 v47, v83, v51
	v_mul_f32_e32 v46, 0xbfb8aa3b, v46
	v_mul_f32_e32 v47, 0xbfb8aa3b, v47
	v_min_f32_e32 v46, 0x42700000, v46
	v_min_f32_e32 v47, 0x42700000, v47
	v_exp_f32_e32 v46, v46
	v_exp_f32_e32 v47, v47
	v_add_f32_e32 v42, v84, v42
	v_mul_f32_e32 v42, 0xbfb8aa3b, v42
	v_add_f32_e32 v46, 1.0, v46
	v_add_f32_e32 v47, 1.0, v47
	v_mul_f32_e32 v50, v46, v47
	v_rcp_f32_e32 v50, v50
	v_min_f32_e32 v42, 0x42700000, v42
	v_exp_f32_e32 v42, v42
	v_add_f32_e32 v34, v85, v34
	v_mul_f32_e32 v47, v47, v50
	v_mul_f32_e32 v50, v46, v50
	v_mul_f32_e32 v46, v80, v47
	v_exp_f32_e32 v51, v46
	v_add_f32_e32 v42, 1.0, v42
	v_mul_f32_e32 v34, 0xbfb8aa3b, v34
	v_min_f32_e32 v34, 0x42700000, v34
	v_fma_f32 v46, -v51, v51, 1.0
	v_max_f32_e32 v46, 0, v46
	v_sqrt_f32_e32 v76, v46
	ds_read2st64_b32 v[46:47], v0 offset0:1 offset1:2
	v_exp_f32_e32 v30, v30
	v_exp_f32_e32 v34, v34
	v_mul_f32_e32 v50, v50, v76
	v_add_f32_e32 v32, v78, v32
	s_waitcnt lgkmcnt(0)
	v_mul_f32_e32 v46, v46, v50
	v_add_f32_e32 v50, v83, v52
	v_mul_f32_e32 v50, 0xbfb8aa3b, v50
	v_min_f32_e32 v50, 0x42700000, v50
	v_exp_f32_e32 v50, v50
	v_add_f32_e32 v30, 1.0, v30
	v_add_f32_e32 v34, 1.0, v34
	v_mul_f32_e32 v32, 0xbfb8aa3b, v32
	v_add_f32_e32 v50, 1.0, v50
	v_mul_f32_e32 v52, v48, v50
	v_rcp_f32_e32 v52, v52
	v_min_f32_e32 v32, 0x42700000, v32
	v_exp_f32_e32 v32, v32
	v_mfma_f32_16x16x32_bf16 v[26:29], v[144:147], v[148:151], v[26:29]
	v_mul_f32_e32 v50, v50, v52
	v_mul_f32_e32 v50, v80, v50
	v_exp_f32_e32 v50, v50
	v_mul_f32_e32 v48, v48, v52
	v_add_f32_e32 v32, 1.0, v32
	v_add_f32_e32 v22, v79, v22
	v_fma_f32 v52, -v50, v50, 1.0
	v_max_f32_e32 v52, 0, v52
	v_sqrt_f32_e32 v52, v52
	ds_write2st64_b32 v0, v51, v50 offset0:129 offset1:130
	v_add_f32_e32 v26, v86, v26
	v_mul_f32_e32 v22, 0xbfb8aa3b, v22
	v_mul_f32_e32 v48, v48, v52
	v_mul_f32_e32 v47, v48, v47
	ds_write2st64_b32 v0, v46, v47 offset0:1 offset1:2
	v_add_f32_e32 v46, v55, v49
	v_add_f32_e32 v47, v83, v53
	v_mul_f32_e32 v46, 0xbfb8aa3b, v46
	v_mul_f32_e32 v47, 0xbfb8aa3b, v47
	v_min_f32_e32 v46, 0x42700000, v46
	v_min_f32_e32 v47, 0x42700000, v47
	v_exp_f32_e32 v46, v46
	v_exp_f32_e32 v47, v47
	ds_read_b32 v49, v0 offset:768
	v_mul_f32_e32 v26, 0xbfb8aa3b, v26
	v_add_f32_e32 v46, 1.0, v46
	v_add_f32_e32 v47, 1.0, v47
	v_mul_f32_e32 v48, v46, v47
	v_rcp_f32_e32 v48, v48
	v_min_f32_e32 v22, 0x42700000, v22
	v_min_f32_e32 v26, 0x42700000, v26
	v_exp_f32_e32 v22, v22
	v_mul_f32_e32 v47, v47, v48
	v_mul_f32_e32 v47, v80, v47
	v_exp_f32_e32 v47, v47
	v_mul_f32_e32 v46, v46, v48
	v_exp_f32_e32 v26, v26
	v_add_f32_e32 v22, 1.0, v22
	v_fma_f32 v48, -v47, v47, 1.0
	v_max_f32_e32 v48, 0, v48
	v_sqrt_f32_e32 v48, v48
	ds_write_b32 v0, v47 offset:33536
	v_add_f32_e32 v26, 1.0, v26
	v_add_f32_e32 v24, v79, v24
	v_mul_f32_e32 v46, v46, v48
	s_waitcnt lgkmcnt(1)
	v_mul_f32_e32 v46, v46, v49
	ds_write_b32 v0, v46 offset:768
	v_mul_f32_e32 v46, v38, v42
	v_rcp_f32_e32 v46, v46
	v_mul_f32_e32 v24, 0xbfb8aa3b, v24
	v_min_f32_e32 v24, 0x42700000, v24
	v_exp_f32_e32 v24, v24
	v_mul_f32_e32 v42, v42, v46
	v_mul_f32_e32 v42, v81, v42
	v_exp_f32_e32 v42, v42
	v_mul_f32_e32 v38, v38, v46
	v_add_f32_e32 v24, 1.0, v24
	v_fma_f32 v46, -v42, v42, 1.0
	v_max_f32_e32 v46, 0, v46
	v_sqrt_f32_e32 v46, v46
	ds_write_b32 v0, v42 offset:32832
	v_mul_f32_e32 v38, v38, v46
	v_mul_f32_e32 v38, v38, v77
	ds_write_b32 v0, v38 offset:64
	v_add_f32_e32 v38, v59, v39
	v_add_f32_e32 v39, v84, v43
	v_mul_f32_e32 v38, 0xbfb8aa3b, v38
	v_mul_f32_e32 v39, 0xbfb8aa3b, v39
	v_min_f32_e32 v38, 0x42700000, v38
	v_min_f32_e32 v39, 0x42700000, v39
	v_exp_f32_e32 v38, v38
	v_exp_f32_e32 v39, v39
	v_add_f32_e32 v38, 1.0, v38
	v_add_f32_e32 v39, 1.0, v39
	v_mul_f32_e32 v42, v38, v39
	v_rcp_f32_e32 v42, v42
	s_nop 0
	v_mul_f32_e32 v39, v39, v42
	v_mul_f32_e32 v42, v38, v42
	v_mul_f32_e32 v38, v81, v39
	v_exp_f32_e32 v43, v38
	s_nop 0
	v_fma_f32 v38, -v43, v43, 1.0
	v_max_f32_e32 v38, 0, v38
	v_sqrt_f32_e32 v46, v38
	ds_read2st64_b32 v[38:39], v93 offset0:1 offset1:2
	v_mul_f32_e32 v42, v42, v46
	s_waitcnt lgkmcnt(0)
	v_mul_f32_e32 v38, v42, v38
	v_add_f32_e32 v42, v84, v44
	v_mul_f32_e32 v42, 0xbfb8aa3b, v42
	v_min_f32_e32 v42, 0x42700000, v42
	v_exp_f32_e32 v42, v42
	s_nop 0
	v_add_f32_e32 v42, 1.0, v42
	v_mul_f32_e32 v44, v40, v42
	v_rcp_f32_e32 v44, v44
	s_nop 0
	v_mul_f32_e32 v42, v42, v44
	v_mul_f32_e32 v42, v81, v42
	v_exp_f32_e32 v42, v42
	v_mul_f32_e32 v40, v40, v44
	v_fma_f32 v44, -v42, v42, 1.0
	v_max_f32_e32 v44, 0, v44
	v_sqrt_f32_e32 v44, v44
	s_nop 0
	v_mul_f32_e32 v40, v40, v44
	v_mul_f32_e32 v39, v40, v39
	ds_write2st64_b32 v93, v38, v39 offset0:1 offset1:2
	v_add_f32_e32 v38, v59, v41
	v_add_f32_e32 v39, v84, v45
	v_mul_f32_e32 v38, 0xbfb8aa3b, v38
	v_mul_f32_e32 v39, 0xbfb8aa3b, v39
	v_min_f32_e32 v38, 0x42700000, v38
	v_min_f32_e32 v39, 0x42700000, v39
	v_exp_f32_e32 v38, v38
	v_exp_f32_e32 v39, v39
	ds_read_b32 v41, v93 offset:768
	v_add_f32_e32 v38, 1.0, v38
	v_add_f32_e32 v39, 1.0, v39
	v_mul_f32_e32 v40, v38, v39
	v_rcp_f32_e32 v40, v40
	s_nop 0
	v_mul_f32_e32 v39, v39, v40
	v_mul_f32_e32 v39, v81, v39
	v_exp_f32_e32 v39, v39
	v_mul_f32_e32 v38, v38, v40
	v_fma_f32 v40, -v39, v39, 1.0
	v_max_f32_e32 v40, 0, v40
	v_sqrt_f32_e32 v40, v40
	ds_write2st64_b32 v93, v42, v39 offset0:130 offset1:131
	v_mul_f32_e32 v38, v38, v40
	s_waitcnt lgkmcnt(1)
; __device__ __forceinline__ float frcp(float x) { return __builtin_amdgcn_rcpf(x); }
; __device__ __forceinline__ void lru_item(const Args& A, Frame& F, int l, int it) {
;     ...
;             for (int nt = 0; nt < 4; ++nt)
; #pragma unroll
;                 for (int r = 0; r < 4; ++r) {
;                     const int si = 16 * w + 4 * fq + r, ch = 16 * nt + fr;
;                     const float d0 = 1.f + __builtin_amdgcn_exp2f(fminf((gacc[nt][r] + bgr[nt]) * -1.4426950408889634f, 60.f));
;                     const float d1 = 1.f + __builtin_amdgcn_exp2f(fminf((gacc[nt + 4][r] + bgi[nt]) * -1.4426950408889634f, 60.f));
;                     const float rr = frcp(d0 * d1);
;                     const float rg = rr * d1, ig = rr * d0;
;                     const float av = __builtin_amdgcn_exp2f(rg * spl[nt]);
;                     const float mult = __builtin_amdgcn_sqrtf(fmaxf(1.f - av * av, 0.f));
;                     const float uu = us[si * 64 + ch];
;                     as[si * 64 + ch] = av;
;                     us[si * 64 + ch] = mult * ig * uu;
;                 }
	v_mul_f32_e32 v38, v38, v41
	ds_write2st64_b32 v93, v38, v43 offset0:3 offset1:129
	v_mul_f32_e32 v38, v30, v34
	v_rcp_f32_e32 v38, v38
	ds_read_b32 v39, v0 offset:128
	v_mul_f32_e32 v34, v34, v38
	v_mul_f32_e32 v34, v82, v34
	v_exp_f32_e32 v34, v34
	v_mul_f32_e32 v30, v30, v38
	v_fma_f32 v38, -v34, v34, 1.0
	v_max_f32_e32 v38, 0, v38
	v_sqrt_f32_e32 v38, v38
	ds_write_b32 v0, v34 offset:32896
	v_mul_f32_e32 v30, v30, v38
	s_waitcnt lgkmcnt(1)
	v_mul_f32_e32 v30, v30, v39
	ds_write_b32 v0, v30 offset:128
	v_add_f32_e32 v30, v78, v31
	v_add_f32_e32 v31, v85, v35
	v_mul_f32_e32 v30, 0xbfb8aa3b, v30
	v_mul_f32_e32 v31, 0xbfb8aa3b, v31
	v_min_f32_e32 v30, 0x42700000, v30
	v_min_f32_e32 v31, 0x42700000, v31
	v_exp_f32_e32 v30, v30
	v_exp_f32_e32 v31, v31
	v_add_f32_e32 v30, 1.0, v30
	v_add_f32_e32 v31, 1.0, v31
	v_mul_f32_e32 v34, v30, v31
	v_rcp_f32_e32 v34, v34
	s_nop 0
	v_mul_f32_e32 v31, v31, v34
	v_mul_f32_e32 v34, v30, v34
	v_mul_f32_e32 v30, v82, v31
	v_exp_f32_e32 v35, v30
	s_nop 0
	v_fma_f32 v30, -v35, v35, 1.0
	v_max_f32_e32 v30, 0, v30
	v_sqrt_f32_e32 v38, v30
	ds_read2st64_b32 v[30:31], v94 offset0:1 offset1:2
	v_mul_f32_e32 v34, v34, v38
	s_waitcnt lgkmcnt(0)
	v_mul_f32_e32 v30, v34, v30
	v_add_f32_e32 v34, v85, v36
	v_mul_f32_e32 v34, 0xbfb8aa3b, v34
	v_min_f32_e32 v34, 0x42700000, v34
	v_exp_f32_e32 v34, v34
	s_nop 0
	v_add_f32_e32 v34, 1.0, v34
	v_mul_f32_e32 v36, v32, v34
	v_rcp_f32_e32 v36, v36
	s_nop 0
	v_mul_f32_e32 v34, v34, v36
	v_mul_f32_e32 v34, v82, v34
	v_exp_f32_e32 v34, v34
	v_mul_f32_e32 v32, v32, v36
	v_fma_f32 v36, -v34, v34, 1.0
	v_max_f32_e32 v36, 0, v36
	v_sqrt_f32_e32 v36, v36
	s_nop 0
	v_mul_f32_e32 v32, v32, v36
	v_mul_f32_e32 v31, v32, v31
	ds_write2st64_b32 v94, v30, v31 offset0:1 offset1:2
	v_add_f32_e32 v30, v78, v33
	v_add_f32_e32 v31, v85, v37
	v_mul_f32_e32 v30, 0xbfb8aa3b, v30
	v_mul_f32_e32 v31, 0xbfb8aa3b, v31
	v_min_f32_e32 v30, 0x42700000, v30
	v_min_f32_e32 v31, 0x42700000, v31
	v_exp_f32_e32 v30, v30
	v_exp_f32_e32 v31, v31
	ds_read_b32 v33, v94 offset:768
	v_add_f32_e32 v30, 1.0, v30
	v_add_f32_e32 v31, 1.0, v31
	v_mul_f32_e32 v32, v30, v31
	v_rcp_f32_e32 v32, v32
	s_nop 0
	v_mul_f32_e32 v31, v31, v32
	v_mul_f32_e32 v31, v82, v31
	v_exp_f32_e32 v31, v31
	v_mul_f32_e32 v30, v30, v32
	v_fma_f32 v32, -v31, v31, 1.0
	v_max_f32_e32 v32, 0, v32
	v_sqrt_f32_e32 v32, v32
	ds_write2st64_b32 v94, v34, v31 offset0:130 offset1:131
	v_mul_f32_e32 v30, v30, v32
	s_waitcnt lgkmcnt(1)
	v_mul_f32_e32 v30, v30, v33
	ds_write2st64_b32 v94, v30, v35 offset0:3 offset1:129
	v_mul_f32_e32 v30, v22, v26
	v_rcp_f32_e32 v30, v30
	ds_read_b32 v31, v0 offset:192
	v_mul_f32_e32 v26, v26, v30
	v_mul_f32_e32 v26, v87, v26
	v_exp_f32_e32 v26, v26
	v_mul_f32_e32 v22, v22, v30
	v_fma_f32 v30, -v26, v26, 1.0
	v_max_f32_e32 v30, 0, v30
	v_sqrt_f32_e32 v30, v30
	ds_write_b32 v0, v26 offset:32960
	v_mul_f32_e32 v22, v22, v30
	s_waitcnt lgkmcnt(1)
	v_mul_f32_e32 v22, v22, v31
	ds_write_b32 v0, v22 offset:192
	v_add_f32_e32 v22, v79, v23
	v_add_f32_e32 v23, v86, v27
	v_mul_f32_e32 v22, 0xbfb8aa3b, v22
	v_mul_f32_e32 v23, 0xbfb8aa3b, v23
	v_min_f32_e32 v22, 0x42700000, v22
	v_min_f32_e32 v23, 0x42700000, v23
	v_exp_f32_e32 v22, v22
	v_exp_f32_e32 v23, v23
	v_add_f32_e32 v22, 1.0, v22
	v_add_f32_e32 v23, 1.0, v23
	v_mul_f32_e32 v26, v22, v23
	v_rcp_f32_e32 v26, v26
	s_nop 0
	v_mul_f32_e32 v23, v23, v26
	v_mul_f32_e32 v26, v22, v26
	v_mul_f32_e32 v22, v87, v23
	v_exp_f32_e32 v27, v22
	s_nop 0
	v_fma_f32 v22, -v27, v27, 1.0
	v_max_f32_e32 v22, 0, v22
	v_sqrt_f32_e32 v30, v22
	ds_read2st64_b32 v[22:23], v95 offset0:1 offset1:2
	v_mul_f32_e32 v26, v26, v30
	s_waitcnt lgkmcnt(0)
	v_mul_f32_e32 v22, v26, v22
	v_add_f32_e32 v26, v86, v28
	v_mul_f32_e32 v26, 0xbfb8aa3b, v26
	v_min_f32_e32 v26, 0x42700000, v26
	v_exp_f32_e32 v26, v26
	s_nop 0
	v_add_f32_e32 v26, 1.0, v26
	v_mul_f32_e32 v28, v24, v26
	v_rcp_f32_e32 v28, v28
	s_nop 0
	v_mul_f32_e32 v26, v26, v28
	v_mul_f32_e32 v26, v87, v26
	v_exp_f32_e32 v26, v26
	v_mul_f32_e32 v24, v24, v28
	v_fma_f32 v28, -v26, v26, 1.0
	v_max_f32_e32 v28, 0, v28
	v_sqrt_f32_e32 v28, v28
	s_nop 0
	v_mul_f32_e32 v24, v24, v28
	v_mul_f32_e32 v23, v24, v23
	ds_write2st64_b32 v95, v22, v23 offset0:1 offset1:2
	v_add_f32_e32 v22, v79, v25
	v_add_f32_e32 v23, v86, v29
	v_mul_f32_e32 v22, 0xbfb8aa3b, v22
	v_mul_f32_e32 v23, 0xbfb8aa3b, v23
	v_min_f32_e32 v22, 0x42700000, v22
	v_min_f32_e32 v23, 0x42700000, v23
	v_exp_f32_e32 v22, v22
	v_exp_f32_e32 v23, v23
	ds_read_b32 v25, v95 offset:768
	v_add_f32_e32 v22, 1.0, v22
	v_add_f32_e32 v23, 1.0, v23
	v_mul_f32_e32 v24, v22, v23
	v_rcp_f32_e32 v24, v24
	s_nop 0
	v_mul_f32_e32 v23, v23, v24
	v_mul_f32_e32 v23, v87, v23
	v_exp_f32_e32 v23, v23
	v_mul_f32_e32 v22, v22, v24
	v_fma_f32 v24, -v23, v23, 1.0
	v_max_f32_e32 v24, 0, v24
	v_sqrt_f32_e32 v24, v24
	ds_write2st64_b32 v95, v26, v23 offset0:130 offset1:131
	v_mul_f32_e32 v22, v22, v24
	s_waitcnt lgkmcnt(1)
	v_mul_f32_e32 v22, v22, v25
	ds_write2st64_b32 v95, v22, v27 offset0:3 offset1:129
	s_waitcnt lgkmcnt(0)
	s_add_i32 s100, s45, -1
	s_bfe_u32 s101, s37, 0x10001
	s_cmp_eq_u32 s101, 0
	s_cbranch_scc1 .Lfz_mc_st
	s_sub_i32 s101, 19, s100
	s_cmp_lt_u32 s100, 2
	s_cbranch_scc0 .Lfz_mc1_st
	s_sub_i32 s101, 1, s100

; __device__ __forceinline__ unsigned pk2(float lo, float hi) { const f32x2_t v = {lo, hi}; const bf16v2_t b = __builtin_convertvector(v, bf16v2_t); return __builtin_bit_cast(unsigned, b); }
; __device__ __forceinline__ float bflo(unsigned u) { return __uint_as_float(u << 16); }
; __device__ __forceinline__ float bfhi(unsigned u) { return __uint_as_float(u & 0xffff0000u); }
; #define ST_LOAD(KS, VS, mc_) do { const int _p0 = 128 * (mc_); _Pragma("unroll") for (int ks = 0; ks < 4; ++ks) { VS[ks] = *(const bf16x8*)(vbase + _p0 + 32 * ks + 8 * fq); \
;         _Pragma("unroll") for (int t = 0; t < 2; ++t) KS[ks][t] = *(const bf16x8*)(kbase + (size_t)(16 * t) * TB + _p0 + 32 * ks + 8 * fq); } } while (0)
; #define ST_STORE(mc_) do { bf16_t* stp = WSB(WS_ST) + ((((size_t)(b * NH + h) * 2 + dir) * NCH + (mc_)) * DV + dvrow) * DK + 32 * dkh + 4 * fq; \
;         _Pragma("unroll") for (int t = 0; t < 2; ++t) { u32x2 o; o.x = pk2(acc[t][0], acc[t][1]); o.y = pk2(acc[t][2], acc[t][3]); *(u32x2*)(stp + 16 * t) = o; } } while (0)
; #define ST_COMPUTE(KS, VS) do { acc[0] *= cdec; acc[1] *= cdec; _Pragma("unroll") for (int ks = 0; ks < 4; ++ks) { const bf16x8 bv = scale8(VS[ks], dec[ks]); \
;         _Pragma("unroll") for (int t = 0; t < 2; ++t) acc[t] = __builtin_amdgcn_mfma_f32_16x16x32_bf16(KS[ks][t], bv, acc[t], 0, 0, 0); } } while (0)
; __device__ __forceinline__ bf16x8 scale8(bf16x8 f, const float (&s)[8]) {
;     u32x4 v = __builtin_bit_cast(u32x4, f);
; #pragma unroll
;     for (int i = 0; i < 4; ++i) v[i] = pk2(bflo(v[i]) * s[2 * i], bfhi(v[i]) * s[2 * i + 1]);
;     return __builtin_bit_cast(bf16x8, v);
; }
; __device__ __forceinline__ void ret_state_item(const Args& A, Frame& F, int l, int it) {
;     ...
;     ST_LOAD(ka, va, ST_MC(0));
;     for (int s2 = 0; s2 < NCH; s2 += 2) {
;         ST_STORE(ST_MC(s2));
;         { const int sn = s2 + 1 < NCH - 1 ? s2 + 1 : NCH - 2; ST_LOAD(kb2, vb2, ST_MC(sn)); }
;         ST_COMPUTE(ka, va);
;         ST_STORE(ST_MC(s2 + 1));
;         if (s2 + 1 == NCH - 1) break;
;         { const int sn = s2 + 2 < NCH - 1 ? s2 + 2 : NCH - 2; ST_LOAD(ka, va, ST_MC(sn)); }
;         ST_COMPUTE(kb2, vb2);
.Lfz_mc_st:
	s_lshl_b32 s101, s100, 14
	s_add_u32 s98, s30, 0x1b0c8000
	s_addc_u32 s99, s31, 0
	s_add_u32 s98, s98, s101
	s_addc_u32 s99, s99, 0
	v_cvt_pk_bf16_f32 v250, v160, v161
	v_cvt_pk_bf16_f32 v251, v162, v163
	v_cvt_pk_bf16_f32 v252, v164, v165
	v_cvt_pk_bf16_f32 v253, v166, v167
	global_store_dwordx2 v243, v[250:251], s[98:99]
	global_store_dwordx2 v243, v[252:253], s[98:99] offset:32
	s_waitcnt vmcnt(9)
	s_cmp_eq_u32 s45, 18
	s_cbranch_scc1 .Lfz_skip
	v_pk_mul_f32 v[160:161], v[160:161], v[168:169] op_sel_hi:[1,0]
	v_pk_mul_f32 v[162:163], v[162:163], v[168:169] op_sel_hi:[1,0]
	v_pk_mul_f32 v[164:165], v[164:165], v[168:169] op_sel_hi:[1,0]
	v_pk_mul_f32 v[166:167], v[166:167], v[168:169] op_sel_hi:[1,0]
	v_lshlrev_b32_e32 v250, 16, v190
	v_and_b32_e32 v251, 0xffff0000, v190
	v_pk_mul_f32 v[250:251], v[250:251], v[152:153]
	v_cvt_pk_bf16_f32 v190, v250, v251
	v_lshlrev_b32_e32 v252, 16, v191
	v_and_b32_e32 v253, 0xffff0000, v191
	v_pk_mul_f32 v[252:253], v[252:253], v[154:155]
	v_cvt_pk_bf16_f32 v191, v252, v253
	v_lshlrev_b32_e32 v250, 16, v192
	v_and_b32_e32 v251, 0xffff0000, v192
	v_pk_mul_f32 v[250:251], v[250:251], v[156:157]
	v_cvt_pk_bf16_f32 v192, v250, v251
	v_lshlrev_b32_e32 v252, 16, v193
	v_and_b32_e32 v253, 0xffff0000, v193
	v_pk_mul_f32 v[252:253], v[252:253], v[158:159]
	v_cvt_pk_bf16_f32 v193, v252, v253
	v_lshlrev_b32_e32 v250, 16, v194
	v_and_b32_e32 v251, 0xffff0000, v194
	v_pk_mul_f32 v[250:251], v[250:251], v[152:153]
	v_pk_mul_f32 v[250:251], v[250:251], v[244:245] op_sel_hi:[1,0]
	v_cvt_pk_bf16_f32 v194, v250, v251
	v_lshlrev_b32_e32 v252, 16, v195
	v_and_b32_e32 v253, 0xffff0000, v195
	v_pk_mul_f32 v[252:253], v[252:253], v[154:155]
	v_pk_mul_f32 v[252:253], v[252:253], v[244:245] op_sel_hi:[1,0]
	v_cvt_pk_bf16_f32 v195, v252, v253
	v_lshlrev_b32_e32 v250, 16, v196
	v_and_b32_e32 v251, 0xffff0000, v196
	v_pk_mul_f32 v[250:251], v[250:251], v[156:157]
	v_pk_mul_f32 v[250:251], v[250:251], v[244:245] op_sel_hi:[1,0]
	v_cvt_pk_bf16_f32 v196, v250, v251
	v_lshlrev_b32_e32 v252, 16, v197
	v_and_b32_e32 v253, 0xffff0000, v197
	v_pk_mul_f32 v[252:253], v[252:253], v[158:159]
	v_pk_mul_f32 v[252:253], v[252:253], v[244:245] op_sel_hi:[1,0]
	v_cvt_pk_bf16_f32 v197, v252, v253
	v_lshlrev_b32_e32 v250, 16, v198
	v_and_b32_e32 v251, 0xffff0000, v198
	v_pk_mul_f32 v[250:251], v[250:251], v[152:153]
	v_pk_mul_f32 v[250:251], v[250:251], v[246:247] op_sel_hi:[1,0]
	v_cvt_pk_bf16_f32 v198, v250, v251
	v_lshlrev_b32_e32 v252, 16, v199
	v_and_b32_e32 v253, 0xffff0000, v199
	v_pk_mul_f32 v[252:253], v[252:253], v[154:155]
	v_pk_mul_f32 v[252:253], v[252:253], v[246:247] op_sel_hi:[1,0]
	v_cvt_pk_bf16_f32 v199, v252, v253
	v_lshlrev_b32_e32 v250, 16, v200
	v_and_b32_e32 v251, 0xffff0000, v200
	v_pk_mul_f32 v[250:251], v[250:251], v[156:157]
	v_pk_mul_f32 v[250:251], v[250:251], v[246:247] op_sel_hi:[1,0]
	v_cvt_pk_bf16_f32 v200, v250, v251
	v_lshlrev_b32_e32 v252, 16, v201
	v_and_b32_e32 v253, 0xffff0000, v201
	v_pk_mul_f32 v[252:253], v[252:253], v[158:159]
	v_pk_mul_f32 v[252:253], v[252:253], v[246:247] op_sel_hi:[1,0]
	v_cvt_pk_bf16_f32 v201, v252, v253
	v_lshlrev_b32_e32 v250, 16, v202
	v_and_b32_e32 v251, 0xffff0000, v202
	v_pk_mul_f32 v[250:251], v[250:251], v[152:153]
	v_pk_mul_f32 v[250:251], v[250:251], v[248:249] op_sel_hi:[1,0]
	v_cvt_pk_bf16_f32 v202, v250, v251
	v_lshlrev_b32_e32 v252, 16, v203
	v_and_b32_e32 v253, 0xffff0000, v203
	v_pk_mul_f32 v[252:253], v[252:253], v[154:155]
	v_pk_mul_f32 v[252:253], v[252:253], v[248:249] op_sel_hi:[1,0]
	v_cvt_pk_bf16_f32 v203, v252, v253
	v_lshlrev_b32_e32 v250, 16, v204
	v_and_b32_e32 v251, 0xffff0000, v204
	v_pk_mul_f32 v[250:251], v[250:251], v[156:157]
	v_pk_mul_f32 v[250:251], v[250:251], v[248:249] op_sel_hi:[1,0]
	v_cvt_pk_bf16_f32 v204, v250, v251
	v_lshlrev_b32_e32 v252, 16, v205
	v_and_b32_e32 v253, 0xffff0000, v205
	v_pk_mul_f32 v[252:253], v[252:253], v[158:159]
	v_pk_mul_f32 v[252:253], v[252:253], v[248:249] op_sel_hi:[1,0]
	v_cvt_pk_bf16_f32 v205, v252, v253
	s_nop 1
	v_mfma_f32_16x16x32_bf16 v[160:163], v[206:209], v[190:193], v[160:163]
	v_mfma_f32_16x16x32_bf16 v[164:167], v[210:213], v[190:193], v[164:167]
	v_mfma_f32_16x16x32_bf16 v[160:163], v[214:217], v[194:197], v[160:163]
	v_mfma_f32_16x16x32_bf16 v[164:167], v[218:221], v[194:197], v[164:167]
	v_mfma_f32_16x16x32_bf16 v[160:163], v[222:225], v[198:201], v[160:163]
	v_mfma_f32_16x16x32_bf16 v[164:167], v[226:229], v[198:201], v[164:167]
	v_mfma_f32_16x16x32_bf16 v[160:163], v[230:233], v[202:205], v[160:163]
	v_mfma_f32_16x16x32_bf16 v[164:167], v[234:237], v[202:205], v[164:167]
; #define LAS __attribute__((address_space(3)))
; __device__ __forceinline__ void lru_item(const Args& A, Frame& F, int l, int it) {
;     ...
;         {
;             const int ch = tid & 63, seg = tid >> 6;
;             float A = 1.f, Bv = 0.f;
; #pragma unroll
;             for (int i = 0; i < 16; ++i) { const int si = 16 * seg + i; const float a = as[si * 64 + ch], bb = us[si * 64 + ch]; A *= a; Bv = a * Bv + bb; }
;             LAS float* sA = segA + (sc & 1) * 1024; LAS float* sB = segB + (sc & 1) * 1024;
;             sA[seg * 64 + ch] = A; sB[seg * 64 + ch] = Bv;
;             __syncthreads();
;             float hv = hcar[(sc & 1) * 64 + ch];
;             for (int s = 0; s < seg; ++s) hv = sA[s * 64 + ch] * hv + sB[s * 64 + ch];
.Lfz_skip:
	ds_read2st64_b32 v[190:191], v96 offset0:128 offset1:129
	ds_read2st64_b32 v[206:207], v96 offset1:1
	ds_read2st64_b32 v[192:193], v96 offset0:130 offset1:131
	ds_read2st64_b32 v[208:209], v96 offset0:2 offset1:3
	ds_read2st64_b32 v[194:195], v96 offset0:132 offset1:133
	ds_read2st64_b32 v[210:211], v96 offset0:4 offset1:5
	ds_read2st64_b32 v[196:197], v96 offset0:134 offset1:135
	ds_read2st64_b32 v[212:213], v96 offset0:6 offset1:7
	ds_read2st64_b32 v[198:199], v96 offset0:136 offset1:137
	ds_read2st64_b32 v[214:215], v96 offset0:8 offset1:9
	ds_read2st64_b32 v[200:201], v96 offset0:138 offset1:139
	ds_read2st64_b32 v[216:217], v96 offset0:10 offset1:11
	ds_read2st64_b32 v[202:203], v96 offset0:140 offset1:141
	ds_read2st64_b32 v[218:219], v96 offset0:12 offset1:13
	s_waitcnt lgkmcnt(12)
	v_mul_f32_e32 v237, v190, v191
	v_fma_f32 v238, 0, v190, v206
	v_fma_f32 v238, v238, v191, v207
	ds_read2st64_b32 v[204:205], v96 offset0:142 offset1:143
	ds_read2st64_b32 v[220:221], v96 offset0:14 offset1:15
	s_waitcnt lgkmcnt(12)
	v_mul_f32_e32 v237, v237, v192
	v_fma_f32 v238, v238, v192, v208
	v_mul_f32_e32 v237, v237, v193
	v_fma_f32 v238, v238, v193, v209
	s_waitcnt lgkmcnt(10)
	v_mul_f32_e32 v237, v237, v194
	v_fma_f32 v238, v238, v194, v210
	v_mul_f32_e32 v237, v237, v195
	v_fma_f32 v238, v238, v195, v211
	s_waitcnt lgkmcnt(8)
	v_mul_f32_e32 v237, v237, v196
	v_fma_f32 v238, v238, v196, v212
	v_mul_f32_e32 v237, v237, v197
	v_fma_f32 v238, v238, v197, v213
	s_waitcnt lgkmcnt(6)
	v_mul_f32_e32 v237, v237, v198
	v_fma_f32 v238, v238, v198, v214
	v_mul_f32_e32 v237, v237, v199
	v_fma_f32 v238, v238, v199, v215
	s_waitcnt lgkmcnt(4)
	v_mul_f32_e32 v237, v237, v200
	v_fma_f32 v238, v238, v200, v216
	v_mul_f32_e32 v237, v237, v201
	v_fma_f32 v238, v238, v201, v217
	s_waitcnt lgkmcnt(2)
	v_mul_f32_e32 v237, v237, v202
	v_fma_f32 v238, v238, v202, v218
	v_mul_f32_e32 v237, v237, v203
	v_fma_f32 v238, v238, v203, v219
	s_waitcnt lgkmcnt(0)
	v_mul_f32_e32 v237, v237, v204
	v_fma_f32 v238, v238, v204, v220
	v_mul_f32_e32 v237, v237, v205
	v_fma_f32 v238, v238, v205, v221
	v_lshl_add_u32 v22, v54, 2, s4
	v_add_u32_e32 v23, 0x19000, v22
	v_add_u32_e32 v22, 0x19800, v22
	ds_write_b32 v22, v238
	v_lshl_add_u32 v22, s2, 8, v92
	ds_write_b32 v23, v237
	v_readfirstlane_b32 s98, v91
	s_waitcnt lgkmcnt(0)
	s_barrier
	ds_read_b32 v22, v22
	v_cndmask_b32_e64 v23, 0, 1, s[78:79]
	v_lshl_add_u32 v23, v23, 12, v129
	v_add_u32_e32 v23, 0xfffff800, v23
	ds_read2st64_b32 v[222:223], v23 offset1:8
	ds_read2st64_b32 v[224:225], v23 offset0:1 offset1:9
	ds_read2st64_b32 v[226:227], v23 offset0:2 offset1:10
	ds_read2st64_b32 v[228:229], v23 offset0:3 offset1:11
	ds_read2st64_b32 v[230:231], v23 offset0:4 offset1:12
	ds_read2st64_b32 v[232:233], v23 offset0:5 offset1:13
	ds_read2st64_b32 v[234:235], v23 offset0:6 offset1:14
	s_waitcnt lgkmcnt(7)
	s_cmp_lt_u32 s98, 1
	s_cbranch_scc1 .Lmy_lru_comb_done
	s_waitcnt lgkmcnt(6)
	v_fma_f32 v22, v22, v222, v223
	s_cmp_lt_u32 s98, 2
	s_cbranch_scc1 .Lmy_lru_comb_done
	s_waitcnt lgkmcnt(5)
	v_fma_f32 v22, v22, v224, v225
	s_cmp_lt_u32 s98, 3
	s_cbranch_scc1 .Lmy_lru_comb_done
	s_waitcnt lgkmcnt(4)
	v_fma_f32 v22, v22, v226, v227
	s_cmp_lt_u32 s98, 4
	s_cbranch_scc1 .Lmy_lru_comb_done
	s_waitcnt lgkmcnt(3)
	v_fma_f32 v22, v22, v228, v229
	s_cmp_lt_u32 s98, 5
	s_cbranch_scc1 .Lmy_lru_comb_done
	s_waitcnt lgkmcnt(2)
	v_fma_f32 v22, v22, v230, v231
	s_cmp_lt_u32 s98, 6
	s_cbranch_scc1 .Lmy_lru_comb_done
	s_waitcnt lgkmcnt(1)
	v_fma_f32 v22, v22, v232, v233
	s_cmp_lt_u32 s98, 7
	s_cbranch_scc1 .Lmy_lru_comb_done
	s_waitcnt lgkmcnt(0)
	v_fma_f32 v22, v22, v234, v235
; __device__ __forceinline__ bf16_t f2bf(float f) { return (bf16_t)(pk2(f, 0.f) & 0xffffu); }
; #define ST_LOAD(KS, VS, mc_) do { const int _p0 = 128 * (mc_); _Pragma("unroll") for (int ks = 0; ks < 4; ++ks) { VS[ks] = *(const bf16x8*)(vbase + _p0 + 32 * ks + 8 * fq); \
;         _Pragma("unroll") for (int t = 0; t < 2; ++t) KS[ks][t] = *(const bf16x8*)(kbase + (size_t)(16 * t) * TB + _p0 + 32 * ks + 8 * fq); } } while (0)
; #define ST_STORE(mc_) do { bf16_t* stp = WSB(WS_ST) + ((((size_t)(b * NH + h) * 2 + dir) * NCH + (mc_)) * DV + dvrow) * DK + 32 * dkh + 4 * fq; \
;         _Pragma("unroll") for (int t = 0; t < 2; ++t) { u32x2 o; o.x = pk2(acc[t][0], acc[t][1]); o.y = pk2(acc[t][2], acc[t][3]); *(u32x2*)(stp + 16 * t) = o; } } while (0)
; #define ST_COMPUTE(KS, VS) do { acc[0] *= cdec; acc[1] *= cdec; _Pragma("unroll") for (int ks = 0; ks < 4; ++ks) { const bf16x8 bv = scale8(VS[ks], dec[ks]); \
;         _Pragma("unroll") for (int t = 0; t < 2; ++t) acc[t] = __builtin_amdgcn_mfma_f32_16x16x32_bf16(KS[ks][t], bv, acc[t], 0, 0, 0); } } while (0)
; __device__ __forceinline__ void ret_state_item(const Args& A, Frame& F, int l, int it) {
;     ...
;     for (int s2 = 0; s2 < NCH; s2 += 2) {
;         ST_STORE(ST_MC(s2));
;         { const int sn = s2 + 1 < NCH - 1 ? s2 + 1 : NCH - 2; ST_LOAD(kb2, vb2, ST_MC(sn)); }
;         ST_COMPUTE(ka, va);
;         ST_STORE(ST_MC(s2 + 1));
;         if (s2 + 1 == NCH - 1) break;
;         { const int sn = s2 + 2 < NCH - 1 ? s2 + 2 : NCH - 2; ST_LOAD(ka, va, ST_MC(sn)); }
; __device__ __forceinline__ void lru_item(const Args& A, Frame& F, int l, int it) {
;     ...
; #pragma unroll
;             for (int i = 0; i < 16; ++i) {
;                 const int si = 16 * seg + i; const float a = as[si * 64 + ch], bb = us[si * 64 + ch];
;                 hv = a * hv + bb;
;                 const int p = dir == 0 ? pbase + si : pbase - si;
;                 hout[(size_t)p * D + ch] = f2bf(hv);
;             }
.Lmy_lru_comb_done:
	v_fma_f32 v22, v22, v190, v206
	v_add_u32_e32 v24, s39, v97
	v_ashrrev_i32_e32 v25, 31, v24
	v_lshlrev_b64 v[24:25], 11, v[24:25]
	v_cvt_pk_bf16_f32 v23, v22, s0
	v_lshl_add_u64 v[24:25], v[60:61], 0, v[24:25]
	global_store_short v[24:25], v23, off
	v_fma_f32 v22, v22, v191, v207
	v_add_u32_e32 v240, s39, v99
	v_ashrrev_i32_e32 v241, 31, v240
	v_lshlrev_b64 v[240:241], 11, v[240:241]
	v_cvt_pk_bf16_f32 v239, v22, s0
	v_lshl_add_u64 v[240:241], v[60:61], 0, v[240:241]
	global_store_short v[240:241], v239, off
	v_fma_f32 v22, v22, v192, v208
	v_add_u32_e32 v24, s39, v101
	v_ashrrev_i32_e32 v25, 31, v24
	v_lshlrev_b64 v[24:25], 11, v[24:25]
	v_cvt_pk_bf16_f32 v23, v22, s0
	v_lshl_add_u64 v[24:25], v[60:61], 0, v[24:25]
	global_store_short v[24:25], v23, off
	v_fma_f32 v22, v22, v193, v209
	v_add_u32_e32 v240, s39, v104
	v_ashrrev_i32_e32 v241, 31, v240
	v_lshlrev_b64 v[240:241], 11, v[240:241]
	v_cvt_pk_bf16_f32 v239, v22, s0
	v_lshl_add_u64 v[240:241], v[60:61], 0, v[240:241]
	global_store_short v[240:241], v239, off
	v_fma_f32 v22, v22, v194, v210
	v_add_u32_e32 v24, s39, v106
	v_ashrrev_i32_e32 v25, 31, v24
	v_lshlrev_b64 v[24:25], 11, v[24:25]
	v_cvt_pk_bf16_f32 v23, v22, s0
	v_lshl_add_u64 v[24:25], v[60:61], 0, v[24:25]
	global_store_short v[24:25], v23, off
	v_fma_f32 v22, v22, v195, v211
	v_add_u32_e32 v240, s39, v108
	v_ashrrev_i32_e32 v241, 31, v240
	v_lshlrev_b64 v[240:241], 11, v[240:241]
	v_cvt_pk_bf16_f32 v239, v22, s0
	v_lshl_add_u64 v[240:241], v[60:61], 0, v[240:241]
	global_store_short v[240:241], v239, off
	v_fma_f32 v22, v22, v196, v212
	v_add_u32_e32 v24, s39, v110
	v_ashrrev_i32_e32 v25, 31, v24
	v_lshlrev_b64 v[24:25], 11, v[24:25]
	v_cvt_pk_bf16_f32 v23, v22, s0
	v_lshl_add_u64 v[24:25], v[60:61], 0, v[24:25]
	global_store_short v[24:25], v23, off
	v_fma_f32 v22, v22, v197, v213
	v_add_u32_e32 v240, s39, v112
	v_ashrrev_i32_e32 v241, 31, v240
	v_lshlrev_b64 v[240:241], 11, v[240:241]
	v_cvt_pk_bf16_f32 v239, v22, s0
	v_lshl_add_u64 v[240:241], v[60:61], 0, v[240:241]
	global_store_short v[240:241], v239, off
	v_fma_f32 v22, v22, v198, v214
	v_add_u32_e32 v24, s39, v114
	v_ashrrev_i32_e32 v25, 31, v24
	v_lshlrev_b64 v[24:25], 11, v[24:25]
	v_cvt_pk_bf16_f32 v23, v22, s0
	v_lshl_add_u64 v[24:25], v[60:61], 0, v[24:25]
	global_store_short v[24:25], v23, off
	v_fma_f32 v22, v22, v199, v215
	v_add_u32_e32 v240, s39, v116
	v_ashrrev_i32_e32 v241, 31, v240
	v_lshlrev_b64 v[240:241], 11, v[240:241]
	v_cvt_pk_bf16_f32 v239, v22, s0
	v_lshl_add_u64 v[240:241], v[60:61], 0, v[240:241]
	global_store_short v[240:241], v239, off
	v_fma_f32 v22, v22, v200, v216
	v_add_u32_e32 v24, s39, v118
	v_ashrrev_i32_e32 v25, 31, v24
	v_lshlrev_b64 v[24:25], 11, v[24:25]
	v_cvt_pk_bf16_f32 v23, v22, s0
	v_lshl_add_u64 v[24:25], v[60:61], 0, v[24:25]
	global_store_short v[24:25], v23, off
	v_fma_f32 v22, v22, v201, v217
	v_add_u32_e32 v240, s39, v120
	v_ashrrev_i32_e32 v241, 31, v240
	v_lshlrev_b64 v[240:241], 11, v[240:241]
	v_cvt_pk_bf16_f32 v239, v22, s0
	v_lshl_add_u64 v[240:241], v[60:61], 0, v[240:241]
	global_store_short v[240:241], v239, off
	v_fma_f32 v22, v22, v202, v218
	v_add_u32_e32 v24, s39, v122
	v_ashrrev_i32_e32 v25, 31, v24
	v_lshlrev_b64 v[24:25], 11, v[24:25]
	v_cvt_pk_bf16_f32 v23, v22, s0
	v_lshl_add_u64 v[24:25], v[60:61], 0, v[24:25]
	global_store_short v[24:25], v23, off
	v_fma_f32 v22, v22, v203, v219
	v_add_u32_e32 v240, s39, v124
	v_ashrrev_i32_e32 v241, 31, v240
	v_lshlrev_b64 v[240:241], 11, v[240:241]
	v_cvt_pk_bf16_f32 v239, v22, s0
	v_lshl_add_u64 v[240:241], v[60:61], 0, v[240:241]
	global_store_short v[240:241], v239, off
	v_fma_f32 v22, v22, v204, v220
	v_add_u32_e32 v24, s39, v126
	v_ashrrev_i32_e32 v25, 31, v24
	v_lshlrev_b64 v[24:25], 11, v[24:25]
	v_cvt_pk_bf16_f32 v23, v22, s0
	v_lshl_add_u64 v[24:25], v[60:61], 0, v[24:25]
	global_store_short v[24:25], v23, off
	v_fma_f32 v22, v22, v205, v221
	v_add_u32_e32 v240, s39, v128
	v_ashrrev_i32_e32 v241, 31, v240
	v_lshlrev_b64 v[240:241], 11, v[240:241]
	v_cvt_pk_bf16_f32 v239, v22, s0
	v_lshl_add_u64 v[240:241], v[60:61], 0, v[240:241]
	global_store_short v[240:241], v239, off
	s_cmp_eq_u32 s45, 18
	s_cbranch_scc1 .Lfz_noload
	s_min_u32 s100, s45, 16
	s_bfe_u32 s101, s37, 0x10001
	s_cmp_eq_u32 s101, 0
	s_cbranch_scc1 .Lfz_mc_nx
	s_sub_i32 s101, 19, s100
	s_cmp_lt_u32 s100, 2
	s_cbranch_scc0 .Lfz_mc1_nx
	s_sub_i32 s101, 1, s100

; __device__ __forceinline__ void lru_item(const Args& A, Frame& F, int l, int it) {
;     ...
;             if (seg == 7) hcar[((sc + 1) & 1) * 64 + ch] = hv;
.Lfz_mc_nx:
	s_lshl_b32 s101, s100, 8
	s_add_u32 s98, s30, 0xd8c8000
	s_addc_u32 s99, s31, 0
	s_add_u32 s98, s98, s101
	s_addc_u32 s99, s99, 0
	global_load_dwordx4 v[190:193], v242, s[98:99]
	global_load_dwordx4 v[194:197], v242, s[98:99] offset:64
	global_load_dwordx4 v[198:201], v242, s[98:99] offset:128
	global_load_dwordx4 v[202:205], v242, s[98:99] offset:192
	s_sub_u32 s98, s98, 0x1200000
	s_subb_u32 s99, s99, 0
	global_load_dwordx4 v[206:209], v169, s[98:99]
	global_load_dwordx4 v[214:217], v169, s[98:99] offset:64
	global_load_dwordx4 v[222:225], v169, s[98:99] offset:128
	global_load_dwordx4 v[230:233], v169, s[98:99] offset:192
	s_add_u32 s98, s98, 0x12000
	s_addc_u32 s99, s99, 0
	global_load_dwordx4 v[210:213], v169, s[98:99]
	global_load_dwordx4 v[218:221], v169, s[98:99] offset:64
	global_load_dwordx4 v[226:229], v169, s[98:99] offset:128
	global_load_dwordx4 v[234:237], v169, s[98:99] offset:192
.Lfz_noload:
	s_and_saveexec_b64 s[4:5], s[12:13]
	s_cbranch_execz .LBB0_62
	s_lshl_b32 s2, s45, 8
	s_and_b32 s2, s2, 0x100
	v_add_u32_e32 v23, s2, v92
	ds_write_b32 v23, v22
	s_branch .LBB0_62
